# cmp1+cmp2 run on their 32 WGs inside the attention phase (flag-gated NSA units, FoX/MoBA units first); one grid barrier and the idle cmp phases removed
# speedup vs baseline: 1.0028x; 1.0028x over previous
.LBB0_1302:
	s_andn2_b64 vcc, exec, s[0:1]
	s_cbranch_vccnz .LBB0_1310
	s_branch .LBB0_1310
.Lcmp1_entry:
	v_readlane_b32 s5, v254, 40
	s_ashr_i32 s0, s5, 4
	s_cmp_lt_u32 s5, 16
	s_mov_b32 s1, 0x11400000
	s_cselect_b32 s4, s1, 0x11d00000
	v_readlane_b32 s8, v254, 41
	v_readlane_b32 s9, v254, 42
	s_add_u32 s12, s8, s4
	v_readlane_b32 s1, v254, 25
	s_addc_u32 s13, s9, 0
	s_add_i32 s2, s0, s1
	s_ashr_i32 s3, s2, 31
	s_lshl_b64 s[6:7], s[2:3], 20
	s_mov_b32 s3, -1
	s_add_u32 s8, s8, s6
	v_mbcnt_lo_u32_b32 v0, s3, 0
	v_mbcnt_hi_u32_b32 v140, s3, v0
	v_lshlrev_b32_e32 v16, 4, v140
	v_add_u32_e32 v2, s63, v16
	v_ashrrev_i32_e32 v0, 31, v2
	v_lshrrev_b32_e32 v0, 22, v0
	v_add_u32_e32 v0, v2, v0
	v_ashrrev_i32_e32 v10, 10, v0
	v_mul_i32_i24_e32 v0, 0x400, v10
	v_sub_u32_e32 v0, v2, v0
	v_lshrrev_b32_e32 v3, 4, v0
	v_bitop3_b32 v0, v3, v0, 32 bitop3:0x6c
	v_ashrrev_i32_e32 v4, 31, v0
	v_lshrrev_b32_e32 v4, 26, v4
	v_add_u32_e32 v4, v0, v4
	v_lshlrev_b32_e32 v3, 3, v10
	v_ashrrev_i32_e32 v11, 6, v4
	v_and_b32_e32 v4, 0xc0, v4
	v_and_b32_e32 v3, -16, v3
	v_sub_u32_e32 v0, v0, v4
	v_add_u32_e32 v3, v11, v3
	v_ashrrev_i16_sdwa v0, v199, sext(v0) dst_sel:DWORD dst_unused:UNUSED_PAD src0_sel:DWORD src1_sel:BYTE_0
	v_lshlrev_b32_e32 v5, 5, v10
	v_bfe_i32 v12, v0, 0, 16
	v_lshlrev_b32_e32 v0, 1, v3
	v_lshrrev_b32_e32 v4, 2, v3
	v_and_b32_e32 v6, 3, v11
	s_mov_b32 s3, 0xfffe0
	v_and_b32_e32 v5, 32, v5
	v_and_b32_e32 v0, 24, v0
	v_and_b32_e32 v4, 4, v4
	v_and_or_b32 v6, v3, s3, v6
	v_or3_b32 v0, v6, v4, v0
	v_add_lshl_u32 v4, v5, v12, 1
	v_add_u32_e32 v2, 0x2000, v2
	v_lshl_add_u32 v90, v3, 11, v4
	v_ashrrev_i32_e32 v3, 31, v2
	v_lshrrev_b32_e32 v3, 22, v3
	v_add_u32_e32 v3, v2, v3
	v_ashrrev_i32_e32 v13, 10, v3
	v_mul_i32_i24_e32 v3, 0x400, v13
	v_sub_u32_e32 v2, v2, v3
	v_lshrrev_b32_e32 v3, 4, v2
	v_bitop3_b32 v2, v3, v2, 32 bitop3:0x6c
	v_lshl_add_u32 v0, v0, 12, v4
	v_ashrrev_i32_e32 v4, 31, v2
	v_lshrrev_b32_e32 v4, 26, v4
	v_lshlrev_b32_e32 v3, 3, v13
	v_add_u32_e32 v4, v2, v4
	s_addc_u32 s9, s9, s7
	s_and_b32 s1, s5, 15
	v_and_b32_e32 v3, -16, v3
	v_ashrrev_i32_e32 v14, 6, v4
	v_add_u32_e32 v3, v14, v3
	v_and_b32_e32 v4, 0xffc0, v4
	v_and_b32_e32 v6, 3, v14
	s_cmp_gt_u32 s1, 7
	v_sub_u32_e32 v2, v2, v4
	v_and_or_b32 v6, v3, s3, v6
	s_cselect_b64 s[6:7], -1, 0
	s_lshl_b32 s3, s1, 1
	v_lshrrev_b16_e32 v4, 7, v2
	s_add_i32 s5, s3, -16
	v_and_b32_e32 v4, 1, v4
	s_cmp_lt_u32 s1, 8
	v_add_u16_e32 v2, v2, v4
	s_cselect_b32 s10, s3, s5
	v_ashrrev_i16_sdwa v2, v199, sext(v2) dst_sel:DWORD dst_unused:UNUSED_PAD src0_sel:DWORD src1_sel:BYTE_0
	s_and_b32 s1, s10, 0xf8
	v_lshlrev_b32_e32 v5, 5, v13
	v_bfe_i32 v15, v2, 0, 16
	v_lshlrev_b32_e32 v2, 1, v3
	v_lshrrev_b32_e32 v4, 2, v3
	s_sub_i32 s3, 16, s1
	v_and_b32_e32 v5, 32, v5
	v_and_b32_e32 v2, 24, v2
	v_and_b32_e32 v4, 4, v4
	s_min_u32 s3, s3, 8
	v_or3_b32 v2, v6, v4, v2
	v_add_lshl_u32 v4, v5, v15, 1
	v_cvt_f32_ubyte0_e32 v5, s3
	v_lshl_add_u32 v92, v3, 11, v4
	v_cndmask_b32_e64 v3, 0, 1, s[6:7]
	v_rcp_iflag_f32_e32 v6, v5
	s_and_b32 s5, s10, 6
	v_readfirstlane_b32 s6, v3
	s_or_b32 s5, s5, s6
	v_cvt_f32_ubyte0_e32 v3, s5
	v_mul_f32_e32 v6, v3, v6
	v_trunc_f32_e32 v6, v6
	v_cvt_u32_f32_e32 v7, v6
	v_lshl_add_u32 v94, v2, 12, v4
	v_fma_f32 v2, -v6, v5, v3
	v_cmp_ge_f32_e64 s[6:7], |v2|, v5
	v_readfirstlane_b32 s11, v7
	s_cmp_lg_u64 s[6:7], 0
	s_addc_u32 s6, s11, 0
	s_mul_i32 s3, s6, s3
	s_sub_i32 s3, s5, s3
	s_and_b32 s11, s3, 0xff
	s_or_b32 s1, s1, s11
	s_and_b32 s3, s6, 0xff
	s_lshl_b32 s15, s1, 19
	s_lshl_b32 s5, s3, 20
	s_add_u32 s8, s8, s5
	s_addc_u32 s9, s9, 0
	s_add_u32 s6, s8, 0x2800000
	s_addc_u32 s7, s9, 0
	s_add_i32 s14, s63, 0
	s_add_i32 m0, s14, 0x10000
	v_mov_b32_e32 v95, v1
	global_load_lds_dwordx4 v0, s[6:7]
	s_add_i32 m0, s14, 0x12000
	s_add_u32 s8, s8, 0x2880000
	global_load_lds_dwordx4 v94, s[6:7]
	s_addc_u32 s9, s9, 0
	s_add_i32 m0, s14, 0x14000
	v_mov_b32_e32 v91, v1
	global_load_lds_dwordx4 v0, s[8:9]
	s_add_i32 m0, s14, 0x16000
	v_mov_b32_e32 v93, v1
	global_load_lds_dwordx4 v94, s[8:9]
	s_add_u32 s8, s12, s15
	s_addc_u32 s9, s13, 0
	s_add_i32 s15, s14, 0x2000
	s_mov_b32 m0, s14
	s_add_u32 s12, s8, 0x40000
	global_load_lds_dwordx4 v90, s[8:9]
	s_mov_b32 m0, s15
	s_addc_u32 s13, s9, 0
	s_add_i32 s16, s14, 0x4000
	global_load_lds_dwordx4 v92, s[8:9]
	s_mov_b32 m0, s16
	s_add_i32 s17, s14, 0x6000
	global_load_lds_dwordx4 v90, s[12:13]
	s_mov_b32 m0, s17
	v_lshl_add_u64 v[8:9], s[6:7], 0, v[0:1]
	global_load_lds_dwordx4 v92, s[12:13]
	v_readlane_b32 s12, v254, 45
	v_readlane_b32 s13, v254, 46
	v_lshl_add_u64 v[6:7], s[6:7], 0, v[94:95]
	v_lshl_add_u64 v[2:3], s[8:9], 0, v[90:91]
	s_and_b64 vcc, exec, s[12:13]
	v_lshl_add_u64 v[4:5], s[8:9], 0, v[92:93]
	s_cbranch_vccnz .LBB0_1305
	s_barrier

.LBB0_1309:
	s_lshl_b32 s5, s1, 8
	s_ashr_i32 s1, s0, 31
	s_lshl_b32 s4, s3, 8
	s_lshl_b64 s[0:1], s[0:1], 21
	v_readlane_b32 s6, v254, 41
	v_readlane_b32 s7, v254, 42
	s_add_u32 s0, s6, s0
	s_addc_u32 s1, s7, s1
	s_lshl_b32 s2, s2, 8
	s_ashr_i32 s3, s2, 31
	s_lshl_b64 s[2:3], s[2:3], 2
	s_add_u32 s2, s6, s2
	s_addc_u32 s3, s7, s3
	v_ashrrev_i32_e32 v0, 4, v140
	s_mov_b32 s6, s66
	s_mov_b32 s7, s67
	s_lshl_b32 s6, s6, 6
	s_add_i32 s6, s6, s5
	s_lshl_b32 s5, s7, 5
	s_add_i32 s5, s5, s4
	v_lshl_add_u32 v142, v0, 3, s5
	v_ashrrev_i32_e32 v143, 31, v142
	v_lshl_add_u64 v[90:91], v[142:143], 2, s[2:3]
	s_mov_b64 s[2:3], 0x400000
	v_lshl_add_u64 v[138:139], v[90:91], 0, s[2:3]
	v_add_co_u32_e32 v90, vcc, s61, v90
	v_add_u32_e32 v140, s6, v141
	s_nop 0
	v_addc_co_u32_e32 v91, vcc, 0, v91, vcc
	global_load_dwordx4 v[90:93], v[90:91], off
	s_nop 0
	global_load_dwordx4 v[94:97], v[138:139], off offset:16
	v_ashrrev_i32_e32 v141, 31, v140
	s_waitcnt vmcnt(0)
	v_pk_add_f32 v[144:145], v[134:135], v[90:91]
	s_nop 0
	v_mul_f32_e32 v0, 0x3d372713, v144
	v_mul_f32_e32 v0, v144, v0
	v_fma_f32 v0, v144, v0, v144
	v_mul_f32_e32 v0, 0x3f4c422a, v0
	v_mul_f32_e32 v0, 0x4038aa3b, v0
	v_exp_f32_e32 v0, v0
	v_pk_add_f32 v[134:135], v[132:133], v[96:97]
	v_pk_add_f32 v[132:133], v[130:131], v[94:95]
	v_pk_add_f32 v[136:137], v[136:137], v[92:93]
	v_add_f32_e32 v0, 1.0, v0
	v_rcp_f32_e32 v130, v0
	v_mul_f32_e32 v0, 0x3d372713, v145
	v_mul_f32_e32 v0, v145, v0
	v_fma_f32 v0, v145, v0, v145
	v_mul_f32_e32 v0, 0x3f4c422a, v0
	v_mul_f32_e32 v0, 0x4038aa3b, v0
	v_exp_f32_e32 v0, v0
	v_pk_mul_f32 v[144:145], v[144:145], 0.5 op_sel_hi:[1,0]
	v_pk_add_f32 v[126:127], v[126:127], v[90:91]
	v_pk_add_f32 v[128:129], v[128:129], v[92:93]
	v_add_f32_e32 v0, 1.0, v0
	v_rcp_f32_e32 v131, v0
	v_mul_f32_e32 v0, 0x3d372713, v136
	v_mul_f32_e32 v0, v136, v0
	v_fma_f32 v0, v136, v0, v136
	v_mul_f32_e32 v0, 0x3f4c422a, v0
	v_mul_f32_e32 v0, 0x4038aa3b, v0
	v_exp_f32_e32 v0, v0
	v_pk_fma_f32 v[130:131], v[130:131], 2.0, 1.0 op_sel_hi:[1,0,0] neg_lo:[1,0,0] neg_hi:[1,0,0]
	v_pk_add_f32 v[122:123], v[122:123], v[94:95]
	v_pk_add_f32 v[130:131], v[130:131], 1.0 op_sel_hi:[1,0]
	v_add_f32_e32 v0, 1.0, v0
	v_pk_mul_f32 v[130:131], v[144:145], v[130:131]
	v_rcp_f32_e32 v144, v0
	v_mul_f32_e32 v0, 0x3d372713, v137
	v_mul_f32_e32 v0, v137, v0
	v_fma_f32 v0, v137, v0, v137
	v_mul_f32_e32 v0, 0x3f4c422a, v0
	v_mul_f32_e32 v0, 0x4038aa3b, v0
	v_exp_f32_e32 v0, v0
	v_pk_mul_f32 v[136:137], v[136:137], 0.5 op_sel_hi:[1,0]
	v_cvt_pk_bf16_f32 v130, v130, v131
	v_pk_add_f32 v[124:125], v[124:125], v[96:97]
	v_add_f32_e32 v0, 1.0, v0
	v_rcp_f32_e32 v145, v0
	v_mul_f32_e32 v0, 0x3d372713, v132
	v_mul_f32_e32 v0, v132, v0
	v_fma_f32 v0, v132, v0, v132
	v_mul_f32_e32 v0, 0x3f4c422a, v0
	v_mul_f32_e32 v0, 0x4038aa3b, v0
	v_exp_f32_e32 v0, v0
	v_pk_fma_f32 v[144:145], v[144:145], 2.0, 1.0 op_sel_hi:[1,0,0] neg_lo:[1,0,0] neg_hi:[1,0,0]
	v_pk_add_f32 v[118:119], v[118:119], v[90:91]
	v_pk_add_f32 v[144:145], v[144:145], 1.0 op_sel_hi:[1,0]
	v_add_f32_e32 v0, 1.0, v0
	v_pk_mul_f32 v[136:137], v[136:137], v[144:145]
	v_pk_add_f32 v[120:121], v[120:121], v[92:93]
	v_cvt_pk_bf16_f32 v131, v136, v137
	v_rcp_f32_e32 v136, v0
	v_mul_f32_e32 v0, 0x3d372713, v133
	v_mul_f32_e32 v0, v133, v0
	v_fma_f32 v0, v133, v0, v133
	v_mul_f32_e32 v0, 0x3f4c422a, v0
	v_mul_f32_e32 v0, 0x4038aa3b, v0
	v_exp_f32_e32 v0, v0
	v_pk_mul_f32 v[132:133], v[132:133], 0.5 op_sel_hi:[1,0]
	v_pk_add_f32 v[114:115], v[114:115], v[94:95]
	v_pk_add_f32 v[116:117], v[116:117], v[96:97]
	v_add_f32_e32 v0, 1.0, v0
	v_rcp_f32_e32 v137, v0
	v_mul_f32_e32 v0, 0x3d372713, v134
	v_mul_f32_e32 v0, v134, v0
	v_fma_f32 v0, v134, v0, v134
	v_mul_f32_e32 v0, 0x3f4c422a, v0
	v_mul_f32_e32 v0, 0x4038aa3b, v0
	v_exp_f32_e32 v0, v0
	v_pk_fma_f32 v[136:137], v[136:137], 2.0, 1.0 op_sel_hi:[1,0,0] neg_lo:[1,0,0] neg_hi:[1,0,0]
	v_pk_add_f32 v[110:111], v[110:111], v[90:91]
	v_pk_add_f32 v[136:137], v[136:137], 1.0 op_sel_hi:[1,0]
	v_add_f32_e32 v0, 1.0, v0
	v_pk_mul_f32 v[132:133], v[132:133], v[136:137]
	v_rcp_f32_e32 v136, v0
	v_mul_f32_e32 v0, 0x3d372713, v135
	v_mul_f32_e32 v0, v135, v0
	v_fma_f32 v0, v135, v0, v135
	v_mul_f32_e32 v0, 0x3f4c422a, v0
	v_mul_f32_e32 v0, 0x4038aa3b, v0
	v_exp_f32_e32 v0, v0
	v_pk_mul_f32 v[134:135], v[134:135], 0.5 op_sel_hi:[1,0]
	v_cvt_pk_bf16_f32 v132, v132, v133
	v_pk_add_f32 v[112:113], v[112:113], v[92:93]
	v_add_f32_e32 v0, 1.0, v0
	v_rcp_f32_e32 v137, v0
	v_mul_f32_e32 v0, 0x3d372713, v126
	v_mul_f32_e32 v0, v126, v0
	v_fma_f32 v0, v126, v0, v126
	v_pk_fma_f32 v[136:137], v[136:137], 2.0, 1.0 op_sel_hi:[1,0,0] neg_lo:[1,0,0] neg_hi:[1,0,0]
	v_mul_f32_e32 v0, 0x3f4c422a, v0
	v_pk_add_f32 v[136:137], v[136:137], 1.0 op_sel_hi:[1,0]
	v_mul_f32_e32 v0, 0x4038aa3b, v0
	v_pk_mul_f32 v[134:135], v[134:135], v[136:137]
	v_exp_f32_e32 v0, v0
	v_cvt_pk_bf16_f32 v133, v134, v135
	v_lshlrev_b64 v[134:135], 9, v[140:141]
	v_lshl_add_u64 v[134:135], s[0:1], 0, v[134:135]
	v_lshl_add_u64 v[136:137], v[142:143], 1, v[134:135]
	s_mov_b64 s[0:1], 0x1ac00000
	v_lshl_add_u64 v[134:135], v[136:137], 0, s[0:1]
	s_mov_b32 s0, 0x1ac00000
	v_add_co_u32_e32 v140, vcc, s0, v136
	v_add_f32_e32 v0, 1.0, v0
	s_nop 0
	v_addc_co_u32_e32 v141, vcc, 0, v137, vcc
	global_store_dwordx4 v[140:141], v[130:133], off
	s_mov_b64 s[0:1], 0x1ac02000
	v_pk_add_f32 v[106:107], v[106:107], v[94:95]
	v_rcp_f32_e32 v130, v0
	v_mul_f32_e32 v0, 0x3d372713, v127
	v_mul_f32_e32 v0, v127, v0
	v_fma_f32 v0, v127, v0, v127
	v_mul_f32_e32 v0, 0x3f4c422a, v0
	v_mul_f32_e32 v0, 0x4038aa3b, v0
	v_exp_f32_e32 v0, v0
	v_pk_mul_f32 v[126:127], v[126:127], 0.5 op_sel_hi:[1,0]
	v_pk_add_f32 v[108:109], v[108:109], v[96:97]
	v_pk_add_f32 v[102:103], v[102:103], v[90:91]
	v_add_f32_e32 v0, 1.0, v0
	v_rcp_f32_e32 v131, v0
	v_mul_f32_e32 v0, 0x3d372713, v128
	v_mul_f32_e32 v0, v128, v0
	v_fma_f32 v0, v128, v0, v128
	v_mul_f32_e32 v0, 0x3f4c422a, v0
	v_mul_f32_e32 v0, 0x4038aa3b, v0
	v_exp_f32_e32 v0, v0
	v_pk_fma_f32 v[130:131], v[130:131], 2.0, 1.0 op_sel_hi:[1,0,0] neg_lo:[1,0,0] neg_hi:[1,0,0]
	v_pk_add_f32 v[104:105], v[104:105], v[92:93]
	v_pk_add_f32 v[130:131], v[130:131], 1.0 op_sel_hi:[1,0]
	v_add_f32_e32 v0, 1.0, v0
	v_pk_mul_f32 v[126:127], v[126:127], v[130:131]
	v_rcp_f32_e32 v130, v0
	v_mul_f32_e32 v0, 0x3d372713, v129
	v_mul_f32_e32 v0, v129, v0
	v_fma_f32 v0, v129, v0, v129
	v_mul_f32_e32 v0, 0x3f4c422a, v0
	v_mul_f32_e32 v0, 0x4038aa3b, v0
	v_exp_f32_e32 v0, v0
	v_pk_mul_f32 v[128:129], v[128:129], 0.5 op_sel_hi:[1,0]
	v_cvt_pk_bf16_f32 v126, v126, v127
	v_pk_add_f32 v[98:99], v[98:99], v[94:95]
	v_add_f32_e32 v0, 1.0, v0
	v_rcp_f32_e32 v131, v0
	v_mul_f32_e32 v0, 0x3d372713, v122
	v_mul_f32_e32 v0, v122, v0
	v_fma_f32 v0, v122, v0, v122
	v_mul_f32_e32 v0, 0x3f4c422a, v0
	v_mul_f32_e32 v0, 0x4038aa3b, v0
	v_exp_f32_e32 v0, v0
	v_pk_fma_f32 v[130:131], v[130:131], 2.0, 1.0 op_sel_hi:[1,0,0] neg_lo:[1,0,0] neg_hi:[1,0,0]
	v_pk_add_f32 v[100:101], v[100:101], v[96:97]
	v_pk_add_f32 v[130:131], v[130:131], 1.0 op_sel_hi:[1,0]
	v_add_f32_e32 v0, 1.0, v0
	v_pk_mul_f32 v[128:129], v[128:129], v[130:131]
	v_pk_add_f32 v[86:87], v[86:87], v[90:91]
	v_cvt_pk_bf16_f32 v127, v128, v129
	v_rcp_f32_e32 v128, v0
	v_mul_f32_e32 v0, 0x3d372713, v123
	v_mul_f32_e32 v0, v123, v0
	v_fma_f32 v0, v123, v0, v123
	v_mul_f32_e32 v0, 0x3f4c422a, v0
	v_mul_f32_e32 v0, 0x4038aa3b, v0
	v_exp_f32_e32 v0, v0
	v_pk_mul_f32 v[122:123], v[122:123], 0.5 op_sel_hi:[1,0]
	v_pk_add_f32 v[88:89], v[88:89], v[92:93]
	v_pk_add_f32 v[82:83], v[82:83], v[94:95]
	v_add_f32_e32 v0, 1.0, v0
	v_rcp_f32_e32 v129, v0
	v_mul_f32_e32 v0, 0x3d372713, v124
	v_mul_f32_e32 v0, v124, v0
	v_fma_f32 v0, v124, v0, v124
	v_mul_f32_e32 v0, 0x3f4c422a, v0
	v_mul_f32_e32 v0, 0x4038aa3b, v0
	v_exp_f32_e32 v0, v0
	v_pk_fma_f32 v[128:129], v[128:129], 2.0, 1.0 op_sel_hi:[1,0,0] neg_lo:[1,0,0] neg_hi:[1,0,0]
	v_pk_add_f32 v[84:85], v[84:85], v[96:97]
	v_pk_add_f32 v[128:129], v[128:129], 1.0 op_sel_hi:[1,0]
	v_add_f32_e32 v0, 1.0, v0
	v_pk_mul_f32 v[122:123], v[122:123], v[128:129]
	v_pk_add_f32 v[78:79], v[78:79], v[90:91]
	v_cvt_pk_bf16_f32 v128, v122, v123
	v_rcp_f32_e32 v122, v0
	v_mul_f32_e32 v0, 0x3d372713, v125
	v_mul_f32_e32 v0, v125, v0
	v_fma_f32 v0, v125, v0, v125
	v_mul_f32_e32 v0, 0x3f4c422a, v0
	v_mul_f32_e32 v0, 0x4038aa3b, v0
	v_exp_f32_e32 v0, v0
	v_pk_mul_f32 v[124:125], v[124:125], 0.5 op_sel_hi:[1,0]
	v_pk_add_f32 v[80:81], v[80:81], v[92:93]
	v_pk_add_f32 v[74:75], v[74:75], v[94:95]
	v_add_f32_e32 v0, 1.0, v0
	v_rcp_f32_e32 v123, v0
	v_mul_f32_e32 v0, 0x3d372713, v118
	v_mul_f32_e32 v0, v118, v0
	v_fma_f32 v0, v118, v0, v118
	v_mul_f32_e32 v0, 0x3f4c422a, v0
	v_pk_fma_f32 v[122:123], v[122:123], 2.0, 1.0 op_sel_hi:[1,0,0] neg_lo:[1,0,0] neg_hi:[1,0,0]
	v_mul_f32_e32 v0, 0x4038aa3b, v0
	v_pk_add_f32 v[122:123], v[122:123], 1.0 op_sel_hi:[1,0]
	v_exp_f32_e32 v0, v0
	v_pk_mul_f32 v[122:123], v[124:125], v[122:123]
	v_pk_add_f32 v[76:77], v[76:77], v[96:97]
	v_cvt_pk_bf16_f32 v129, v122, v123
	v_lshl_add_u64 v[122:123], v[136:137], 0, s[0:1]
	s_mov_b32 s0, 0x1ac02000
	v_add_co_u32_e32 v124, vcc, s0, v136
	v_add_f32_e32 v0, 1.0, v0
	s_nop 0
	v_addc_co_u32_e32 v125, vcc, 0, v137, vcc
	global_store_dwordx4 v[124:125], v[126:129], off
	v_rcp_f32_e32 v124, v0
	v_mul_f32_e32 v0, 0x3d372713, v119
	v_mul_f32_e32 v0, v119, v0
	v_fma_f32 v0, v119, v0, v119
	v_mul_f32_e32 v0, 0x3f4c422a, v0
	v_mul_f32_e32 v0, 0x4038aa3b, v0
	v_exp_f32_e32 v0, v0
	v_pk_mul_f32 v[118:119], v[118:119], 0.5 op_sel_hi:[1,0]
	s_mov_b64 s[0:1], 0x1ac04000
	v_pk_add_f32 v[70:71], v[70:71], v[90:91]
	v_add_f32_e32 v0, 1.0, v0
	v_rcp_f32_e32 v125, v0
	v_mul_f32_e32 v0, 0x3d372713, v120
	v_mul_f32_e32 v0, v120, v0
	v_fma_f32 v0, v120, v0, v120
	v_mul_f32_e32 v0, 0x3f4c422a, v0
	v_mul_f32_e32 v0, 0x4038aa3b, v0
	v_exp_f32_e32 v0, v0
	v_pk_fma_f32 v[124:125], v[124:125], 2.0, 1.0 op_sel_hi:[1,0,0] neg_lo:[1,0,0] neg_hi:[1,0,0]
	v_pk_add_f32 v[72:73], v[72:73], v[92:93]
	v_pk_add_f32 v[124:125], v[124:125], 1.0 op_sel_hi:[1,0]
	v_add_f32_e32 v0, 1.0, v0
	v_pk_mul_f32 v[118:119], v[118:119], v[124:125]
	v_rcp_f32_e32 v124, v0
	v_mul_f32_e32 v0, 0x3d372713, v121
	v_mul_f32_e32 v0, v121, v0
	v_fma_f32 v0, v121, v0, v121
	v_mul_f32_e32 v0, 0x3f4c422a, v0
	v_mul_f32_e32 v0, 0x4038aa3b, v0
	v_exp_f32_e32 v0, v0
	v_pk_mul_f32 v[120:121], v[120:121], 0.5 op_sel_hi:[1,0]
	v_cvt_pk_bf16_f32 v118, v118, v119
	v_pk_add_f32 v[66:67], v[66:67], v[94:95]
	v_add_f32_e32 v0, 1.0, v0
	v_rcp_f32_e32 v125, v0
	v_mul_f32_e32 v0, 0x3d372713, v114
	v_mul_f32_e32 v0, v114, v0
	v_fma_f32 v0, v114, v0, v114
	v_mul_f32_e32 v0, 0x3f4c422a, v0
	v_mul_f32_e32 v0, 0x4038aa3b, v0
	v_exp_f32_e32 v0, v0
	v_pk_fma_f32 v[124:125], v[124:125], 2.0, 1.0 op_sel_hi:[1,0,0] neg_lo:[1,0,0] neg_hi:[1,0,0]
	v_pk_add_f32 v[68:69], v[68:69], v[96:97]
	v_pk_add_f32 v[124:125], v[124:125], 1.0 op_sel_hi:[1,0]
	v_add_f32_e32 v0, 1.0, v0
	v_pk_mul_f32 v[120:121], v[120:121], v[124:125]
	s_nop 0
	v_cvt_pk_bf16_f32 v119, v120, v121
	v_rcp_f32_e32 v120, v0
	v_mul_f32_e32 v0, 0x3d372713, v115
	v_mul_f32_e32 v0, v115, v0
	v_fma_f32 v0, v115, v0, v115
	v_mul_f32_e32 v0, 0x3f4c422a, v0
	v_mul_f32_e32 v0, 0x4038aa3b, v0
	v_exp_f32_e32 v0, v0
	v_pk_mul_f32 v[114:115], v[114:115], 0.5 op_sel_hi:[1,0]
	v_add_f32_e32 v0, 1.0, v0
	v_rcp_f32_e32 v121, v0
	v_mul_f32_e32 v0, 0x3d372713, v116
	v_mul_f32_e32 v0, v116, v0
	v_fma_f32 v0, v116, v0, v116
	v_mul_f32_e32 v0, 0x3f4c422a, v0
	v_mul_f32_e32 v0, 0x4038aa3b, v0
	v_exp_f32_e32 v0, v0
	v_pk_fma_f32 v[120:121], v[120:121], 2.0, 1.0 op_sel_hi:[1,0,0] neg_lo:[1,0,0] neg_hi:[1,0,0]
	v_add_f32_e32 v0, 1.0, v0
	v_pk_add_f32 v[120:121], v[120:121], 1.0 op_sel_hi:[1,0]
	s_nop 0
	v_pk_mul_f32 v[114:115], v[114:115], v[120:121]
	s_nop 0
	v_cvt_pk_bf16_f32 v120, v114, v115
	v_rcp_f32_e32 v114, v0
	v_mul_f32_e32 v0, 0x3d372713, v117
	v_mul_f32_e32 v0, v117, v0
	v_fma_f32 v0, v117, v0, v117
	v_mul_f32_e32 v0, 0x3f4c422a, v0
	v_mul_f32_e32 v0, 0x4038aa3b, v0
	v_exp_f32_e32 v0, v0
	v_pk_mul_f32 v[116:117], v[116:117], 0.5 op_sel_hi:[1,0]
	v_add_f32_e32 v0, 1.0, v0
	v_rcp_f32_e32 v115, v0
	v_mul_f32_e32 v0, 0x3d372713, v110
	v_mul_f32_e32 v0, v110, v0
	v_fma_f32 v0, v110, v0, v110
	v_mul_f32_e32 v0, 0x3f4c422a, v0
	v_pk_fma_f32 v[114:115], v[114:115], 2.0, 1.0 op_sel_hi:[1,0,0] neg_lo:[1,0,0] neg_hi:[1,0,0]
	v_mul_f32_e32 v0, 0x4038aa3b, v0
	v_pk_add_f32 v[114:115], v[114:115], 1.0 op_sel_hi:[1,0]
	v_exp_f32_e32 v0, v0
	v_pk_mul_f32 v[114:115], v[116:117], v[114:115]
	v_add_f32_e32 v0, 1.0, v0
	v_cvt_pk_bf16_f32 v121, v114, v115
	v_lshl_add_u64 v[114:115], v[136:137], 0, s[0:1]
	s_mov_b32 s0, 0x1ac04000
	v_add_co_u32_e32 v116, vcc, s0, v136
	s_mov_b64 s[0:1], 0x1ac06000
	s_nop 0
	v_addc_co_u32_e32 v117, vcc, 0, v137, vcc
	global_store_dwordx4 v[116:117], v[118:121], off
	v_rcp_f32_e32 v116, v0
	v_mul_f32_e32 v0, 0x3d372713, v111
	v_mul_f32_e32 v0, v111, v0
	v_fma_f32 v0, v111, v0, v111
	v_mul_f32_e32 v0, 0x3f4c422a, v0
	v_mul_f32_e32 v0, 0x4038aa3b, v0
	v_exp_f32_e32 v0, v0
	v_pk_mul_f32 v[110:111], v[110:111], 0.5 op_sel_hi:[1,0]
	v_add_f32_e32 v0, 1.0, v0
	v_rcp_f32_e32 v117, v0
	v_mul_f32_e32 v0, 0x3d372713, v112
	v_mul_f32_e32 v0, v112, v0
	v_fma_f32 v0, v112, v0, v112
	v_mul_f32_e32 v0, 0x3f4c422a, v0
	v_mul_f32_e32 v0, 0x4038aa3b, v0
	v_exp_f32_e32 v0, v0
	v_pk_fma_f32 v[116:117], v[116:117], 2.0, 1.0 op_sel_hi:[1,0,0] neg_lo:[1,0,0] neg_hi:[1,0,0]
	v_add_f32_e32 v0, 1.0, v0
	v_pk_add_f32 v[116:117], v[116:117], 1.0 op_sel_hi:[1,0]
	s_nop 0
	v_pk_mul_f32 v[110:111], v[110:111], v[116:117]
	v_rcp_f32_e32 v116, v0
	v_mul_f32_e32 v0, 0x3d372713, v113
	v_mul_f32_e32 v0, v113, v0
	v_fma_f32 v0, v113, v0, v113
	v_mul_f32_e32 v0, 0x3f4c422a, v0
	v_mul_f32_e32 v0, 0x4038aa3b, v0
	v_exp_f32_e32 v0, v0
	v_pk_mul_f32 v[112:113], v[112:113], 0.5 op_sel_hi:[1,0]
	v_cvt_pk_bf16_f32 v110, v110, v111
	v_add_f32_e32 v0, 1.0, v0
	v_rcp_f32_e32 v117, v0
	v_mul_f32_e32 v0, 0x3d372713, v106
	v_mul_f32_e32 v0, v106, v0
	v_fma_f32 v0, v106, v0, v106
	v_mul_f32_e32 v0, 0x3f4c422a, v0
	v_mul_f32_e32 v0, 0x4038aa3b, v0
	v_exp_f32_e32 v0, v0
	v_pk_fma_f32 v[116:117], v[116:117], 2.0, 1.0 op_sel_hi:[1,0,0] neg_lo:[1,0,0] neg_hi:[1,0,0]
	v_add_f32_e32 v0, 1.0, v0
	v_pk_add_f32 v[116:117], v[116:117], 1.0 op_sel_hi:[1,0]
	s_nop 0
	v_pk_mul_f32 v[112:113], v[112:113], v[116:117]
	s_nop 0
	v_cvt_pk_bf16_f32 v111, v112, v113
	v_rcp_f32_e32 v112, v0
	v_mul_f32_e32 v0, 0x3d372713, v107
	v_mul_f32_e32 v0, v107, v0
	v_fma_f32 v0, v107, v0, v107
	v_mul_f32_e32 v0, 0x3f4c422a, v0
	v_mul_f32_e32 v0, 0x4038aa3b, v0
	v_exp_f32_e32 v0, v0
	v_pk_mul_f32 v[106:107], v[106:107], 0.5 op_sel_hi:[1,0]
	v_add_f32_e32 v0, 1.0, v0
	v_rcp_f32_e32 v113, v0
	v_mul_f32_e32 v0, 0x3d372713, v108
	v_mul_f32_e32 v0, v108, v0
	v_fma_f32 v0, v108, v0, v108
	v_mul_f32_e32 v0, 0x3f4c422a, v0
	v_mul_f32_e32 v0, 0x4038aa3b, v0
	v_exp_f32_e32 v0, v0
	v_pk_fma_f32 v[112:113], v[112:113], 2.0, 1.0 op_sel_hi:[1,0,0] neg_lo:[1,0,0] neg_hi:[1,0,0]
	v_add_f32_e32 v0, 1.0, v0
	v_pk_add_f32 v[112:113], v[112:113], 1.0 op_sel_hi:[1,0]
	s_nop 0
	v_pk_mul_f32 v[106:107], v[106:107], v[112:113]
	s_nop 0
	v_cvt_pk_bf16_f32 v112, v106, v107
	v_rcp_f32_e32 v106, v0
	v_mul_f32_e32 v0, 0x3d372713, v109
	v_mul_f32_e32 v0, v109, v0
	v_fma_f32 v0, v109, v0, v109
	v_mul_f32_e32 v0, 0x3f4c422a, v0
	v_mul_f32_e32 v0, 0x4038aa3b, v0
	v_exp_f32_e32 v0, v0
	v_pk_mul_f32 v[108:109], v[108:109], 0.5 op_sel_hi:[1,0]
	v_add_f32_e32 v0, 1.0, v0
	v_rcp_f32_e32 v107, v0
	v_mul_f32_e32 v0, 0x3d372713, v102
	v_mul_f32_e32 v0, v102, v0
	v_fma_f32 v0, v102, v0, v102
	v_mul_f32_e32 v0, 0x3f4c422a, v0
	v_pk_fma_f32 v[106:107], v[106:107], 2.0, 1.0 op_sel_hi:[1,0,0] neg_lo:[1,0,0] neg_hi:[1,0,0]
	v_mul_f32_e32 v0, 0x4038aa3b, v0
	v_pk_add_f32 v[106:107], v[106:107], 1.0 op_sel_hi:[1,0]
	v_exp_f32_e32 v0, v0
	v_pk_mul_f32 v[106:107], v[108:109], v[106:107]
	v_add_f32_e32 v0, 1.0, v0
	v_cvt_pk_bf16_f32 v113, v106, v107
	v_lshl_add_u64 v[106:107], v[136:137], 0, s[0:1]
	s_mov_b32 s0, 0x1ac06000
	v_add_co_u32_e32 v108, vcc, s0, v136
	s_mov_b64 s[0:1], 0x1ac10000
	s_nop 0
	v_addc_co_u32_e32 v109, vcc, 0, v137, vcc
	global_store_dwordx4 v[108:109], v[110:113], off
	v_rcp_f32_e32 v108, v0
	v_mul_f32_e32 v0, 0x3d372713, v103
	v_mul_f32_e32 v0, v103, v0
	v_fma_f32 v0, v103, v0, v103
	v_mul_f32_e32 v0, 0x3f4c422a, v0
	v_mul_f32_e32 v0, 0x4038aa3b, v0
	v_exp_f32_e32 v0, v0
	v_pk_mul_f32 v[102:103], v[102:103], 0.5 op_sel_hi:[1,0]
	v_add_f32_e32 v0, 1.0, v0
	v_rcp_f32_e32 v109, v0
	v_mul_f32_e32 v0, 0x3d372713, v104
	v_mul_f32_e32 v0, v104, v0
	v_fma_f32 v0, v104, v0, v104
	v_mul_f32_e32 v0, 0x3f4c422a, v0
	v_mul_f32_e32 v0, 0x4038aa3b, v0
	v_exp_f32_e32 v0, v0
	v_pk_fma_f32 v[108:109], v[108:109], 2.0, 1.0 op_sel_hi:[1,0,0] neg_lo:[1,0,0] neg_hi:[1,0,0]
	v_add_f32_e32 v0, 1.0, v0
	v_pk_add_f32 v[108:109], v[108:109], 1.0 op_sel_hi:[1,0]
	s_nop 0
	v_pk_mul_f32 v[102:103], v[102:103], v[108:109]
	v_rcp_f32_e32 v108, v0
	v_mul_f32_e32 v0, 0x3d372713, v105
	v_mul_f32_e32 v0, v105, v0
	v_fma_f32 v0, v105, v0, v105
	v_mul_f32_e32 v0, 0x3f4c422a, v0
	v_mul_f32_e32 v0, 0x4038aa3b, v0
	v_exp_f32_e32 v0, v0
	v_pk_mul_f32 v[104:105], v[104:105], 0.5 op_sel_hi:[1,0]
	v_cvt_pk_bf16_f32 v102, v102, v103
	v_add_f32_e32 v0, 1.0, v0
	v_rcp_f32_e32 v109, v0
	v_mul_f32_e32 v0, 0x3d372713, v98
	v_mul_f32_e32 v0, v98, v0
	v_fma_f32 v0, v98, v0, v98
	v_mul_f32_e32 v0, 0x3f4c422a, v0
	v_mul_f32_e32 v0, 0x4038aa3b, v0
	v_exp_f32_e32 v0, v0
	v_pk_fma_f32 v[108:109], v[108:109], 2.0, 1.0 op_sel_hi:[1,0,0] neg_lo:[1,0,0] neg_hi:[1,0,0]
	v_add_f32_e32 v0, 1.0, v0
	v_pk_add_f32 v[108:109], v[108:109], 1.0 op_sel_hi:[1,0]
	s_nop 0
	v_pk_mul_f32 v[104:105], v[104:105], v[108:109]
	s_nop 0
	v_cvt_pk_bf16_f32 v103, v104, v105
	v_rcp_f32_e32 v104, v0
	v_mul_f32_e32 v0, 0x3d372713, v99
	v_mul_f32_e32 v0, v99, v0
	v_fma_f32 v0, v99, v0, v99
	v_mul_f32_e32 v0, 0x3f4c422a, v0
	v_mul_f32_e32 v0, 0x4038aa3b, v0
	v_exp_f32_e32 v0, v0
	v_pk_mul_f32 v[98:99], v[98:99], 0.5 op_sel_hi:[1,0]
	v_add_f32_e32 v0, 1.0, v0
	v_rcp_f32_e32 v105, v0
	v_mul_f32_e32 v0, 0x3d372713, v100
	v_mul_f32_e32 v0, v100, v0
	v_fma_f32 v0, v100, v0, v100
	v_mul_f32_e32 v0, 0x3f4c422a, v0
	v_mul_f32_e32 v0, 0x4038aa3b, v0
	v_exp_f32_e32 v0, v0
	v_pk_fma_f32 v[104:105], v[104:105], 2.0, 1.0 op_sel_hi:[1,0,0] neg_lo:[1,0,0] neg_hi:[1,0,0]
	v_add_f32_e32 v0, 1.0, v0
	v_pk_add_f32 v[104:105], v[104:105], 1.0 op_sel_hi:[1,0]
	s_nop 0
	v_pk_mul_f32 v[98:99], v[98:99], v[104:105]
	s_nop 0
	v_cvt_pk_bf16_f32 v104, v98, v99
	v_rcp_f32_e32 v98, v0
	v_mul_f32_e32 v0, 0x3d372713, v101
	v_mul_f32_e32 v0, v101, v0
	v_fma_f32 v0, v101, v0, v101
	v_mul_f32_e32 v0, 0x3f4c422a, v0
	v_mul_f32_e32 v0, 0x4038aa3b, v0
	v_exp_f32_e32 v0, v0
	v_pk_mul_f32 v[100:101], v[100:101], 0.5 op_sel_hi:[1,0]
	v_add_f32_e32 v0, 1.0, v0
	v_rcp_f32_e32 v99, v0
	v_mul_f32_e32 v0, 0x3d372713, v86
	v_mul_f32_e32 v0, v86, v0
	v_fma_f32 v0, v86, v0, v86
	v_mul_f32_e32 v0, 0x3f4c422a, v0
	v_pk_fma_f32 v[98:99], v[98:99], 2.0, 1.0 op_sel_hi:[1,0,0] neg_lo:[1,0,0] neg_hi:[1,0,0]
	v_mul_f32_e32 v0, 0x4038aa3b, v0
	v_pk_add_f32 v[98:99], v[98:99], 1.0 op_sel_hi:[1,0]
	v_exp_f32_e32 v0, v0
	v_pk_mul_f32 v[98:99], v[100:101], v[98:99]
	v_add_f32_e32 v0, 1.0, v0
	v_cvt_pk_bf16_f32 v105, v98, v99
	v_lshl_add_u64 v[98:99], v[136:137], 0, s[0:1]
	s_mov_b32 s0, 0x1ac10000
	v_add_co_u32_e32 v100, vcc, s0, v136
	s_mov_b64 s[0:1], 0x1ac12000
	s_nop 0
	v_addc_co_u32_e32 v101, vcc, 0, v137, vcc
	global_store_dwordx4 v[100:101], v[102:105], off
	v_rcp_f32_e32 v100, v0
	v_mul_f32_e32 v0, 0x3d372713, v87
	v_mul_f32_e32 v0, v87, v0
	v_fma_f32 v0, v87, v0, v87
	v_mul_f32_e32 v0, 0x3f4c422a, v0
	v_mul_f32_e32 v0, 0x4038aa3b, v0
	v_exp_f32_e32 v0, v0
	v_pk_mul_f32 v[86:87], v[86:87], 0.5 op_sel_hi:[1,0]
	v_add_f32_e32 v0, 1.0, v0
	v_rcp_f32_e32 v101, v0
	v_mul_f32_e32 v0, 0x3d372713, v88
	v_mul_f32_e32 v0, v88, v0
	v_fma_f32 v0, v88, v0, v88
	v_mul_f32_e32 v0, 0x3f4c422a, v0
	v_mul_f32_e32 v0, 0x4038aa3b, v0
	v_exp_f32_e32 v0, v0
	v_pk_fma_f32 v[100:101], v[100:101], 2.0, 1.0 op_sel_hi:[1,0,0] neg_lo:[1,0,0] neg_hi:[1,0,0]
	v_add_f32_e32 v0, 1.0, v0
	v_pk_add_f32 v[100:101], v[100:101], 1.0 op_sel_hi:[1,0]
	s_nop 0
	v_pk_mul_f32 v[86:87], v[86:87], v[100:101]
	v_rcp_f32_e32 v100, v0
	v_mul_f32_e32 v0, 0x3d372713, v89
	v_mul_f32_e32 v0, v89, v0
	v_fma_f32 v0, v89, v0, v89
	v_mul_f32_e32 v0, 0x3f4c422a, v0
	v_mul_f32_e32 v0, 0x4038aa3b, v0
	v_exp_f32_e32 v0, v0
	v_pk_mul_f32 v[88:89], v[88:89], 0.5 op_sel_hi:[1,0]
	v_cvt_pk_bf16_f32 v86, v86, v87
	v_add_f32_e32 v0, 1.0, v0
	v_rcp_f32_e32 v101, v0
	v_mul_f32_e32 v0, 0x3d372713, v82
	v_mul_f32_e32 v0, v82, v0
	v_fma_f32 v0, v82, v0, v82
	v_mul_f32_e32 v0, 0x3f4c422a, v0
	v_mul_f32_e32 v0, 0x4038aa3b, v0
	v_exp_f32_e32 v0, v0
	v_pk_fma_f32 v[100:101], v[100:101], 2.0, 1.0 op_sel_hi:[1,0,0] neg_lo:[1,0,0] neg_hi:[1,0,0]
	v_add_f32_e32 v0, 1.0, v0
	v_pk_add_f32 v[100:101], v[100:101], 1.0 op_sel_hi:[1,0]
	s_nop 0
	v_pk_mul_f32 v[88:89], v[88:89], v[100:101]
	s_nop 0
	v_cvt_pk_bf16_f32 v87, v88, v89
	v_rcp_f32_e32 v88, v0
	v_mul_f32_e32 v0, 0x3d372713, v83
	v_mul_f32_e32 v0, v83, v0
	v_fma_f32 v0, v83, v0, v83
	v_mul_f32_e32 v0, 0x3f4c422a, v0
	v_mul_f32_e32 v0, 0x4038aa3b, v0
	v_exp_f32_e32 v0, v0
	v_pk_mul_f32 v[82:83], v[82:83], 0.5 op_sel_hi:[1,0]
	v_add_f32_e32 v0, 1.0, v0
	v_rcp_f32_e32 v89, v0
	v_mul_f32_e32 v0, 0x3d372713, v84
	v_mul_f32_e32 v0, v84, v0
	v_fma_f32 v0, v84, v0, v84
	v_mul_f32_e32 v0, 0x3f4c422a, v0
	v_mul_f32_e32 v0, 0x4038aa3b, v0
	v_exp_f32_e32 v0, v0
	v_pk_fma_f32 v[88:89], v[88:89], 2.0, 1.0 op_sel_hi:[1,0,0] neg_lo:[1,0,0] neg_hi:[1,0,0]
	v_add_f32_e32 v0, 1.0, v0
	v_pk_add_f32 v[88:89], v[88:89], 1.0 op_sel_hi:[1,0]
	s_nop 0
	v_pk_mul_f32 v[82:83], v[82:83], v[88:89]
	s_nop 0
	v_cvt_pk_bf16_f32 v88, v82, v83
	v_rcp_f32_e32 v82, v0
	v_mul_f32_e32 v0, 0x3d372713, v85
	v_mul_f32_e32 v0, v85, v0
	v_fma_f32 v0, v85, v0, v85
	v_mul_f32_e32 v0, 0x3f4c422a, v0
	v_mul_f32_e32 v0, 0x4038aa3b, v0
	v_exp_f32_e32 v0, v0
	v_pk_mul_f32 v[84:85], v[84:85], 0.5 op_sel_hi:[1,0]
	v_add_f32_e32 v0, 1.0, v0
	v_rcp_f32_e32 v83, v0
	v_mul_f32_e32 v0, 0x3d372713, v78
	v_mul_f32_e32 v0, v78, v0
	v_fma_f32 v0, v78, v0, v78
	v_mul_f32_e32 v0, 0x3f4c422a, v0
	v_pk_fma_f32 v[82:83], v[82:83], 2.0, 1.0 op_sel_hi:[1,0,0] neg_lo:[1,0,0] neg_hi:[1,0,0]
	v_mul_f32_e32 v0, 0x4038aa3b, v0
	v_pk_add_f32 v[82:83], v[82:83], 1.0 op_sel_hi:[1,0]
	v_exp_f32_e32 v0, v0
	v_pk_mul_f32 v[82:83], v[84:85], v[82:83]
	v_add_f32_e32 v0, 1.0, v0
	v_cvt_pk_bf16_f32 v89, v82, v83
	v_lshl_add_u64 v[82:83], v[136:137], 0, s[0:1]
	s_mov_b32 s0, 0x1ac12000
	v_add_co_u32_e32 v84, vcc, s0, v136
	s_mov_b64 s[0:1], 0x1ac14000
	s_nop 0
	v_addc_co_u32_e32 v85, vcc, 0, v137, vcc
	global_store_dwordx4 v[84:85], v[86:89], off
	v_rcp_f32_e32 v84, v0
	v_mul_f32_e32 v0, 0x3d372713, v79
	v_mul_f32_e32 v0, v79, v0
	v_fma_f32 v0, v79, v0, v79
	v_mul_f32_e32 v0, 0x3f4c422a, v0
	v_mul_f32_e32 v0, 0x4038aa3b, v0
	v_exp_f32_e32 v0, v0
	v_pk_mul_f32 v[78:79], v[78:79], 0.5 op_sel_hi:[1,0]
	v_add_f32_e32 v0, 1.0, v0
	v_rcp_f32_e32 v85, v0
	v_mul_f32_e32 v0, 0x3d372713, v80
	v_mul_f32_e32 v0, v80, v0
	v_fma_f32 v0, v80, v0, v80
	v_mul_f32_e32 v0, 0x3f4c422a, v0
	v_mul_f32_e32 v0, 0x4038aa3b, v0
	v_exp_f32_e32 v0, v0
	v_pk_fma_f32 v[84:85], v[84:85], 2.0, 1.0 op_sel_hi:[1,0,0] neg_lo:[1,0,0] neg_hi:[1,0,0]
	v_add_f32_e32 v0, 1.0, v0
	v_pk_add_f32 v[84:85], v[84:85], 1.0 op_sel_hi:[1,0]
	s_nop 0
	v_pk_mul_f32 v[78:79], v[78:79], v[84:85]
	v_rcp_f32_e32 v84, v0
	v_mul_f32_e32 v0, 0x3d372713, v81
	v_mul_f32_e32 v0, v81, v0
	v_fma_f32 v0, v81, v0, v81
	v_mul_f32_e32 v0, 0x3f4c422a, v0
	v_mul_f32_e32 v0, 0x4038aa3b, v0
	v_exp_f32_e32 v0, v0
	v_pk_mul_f32 v[80:81], v[80:81], 0.5 op_sel_hi:[1,0]
	v_cvt_pk_bf16_f32 v78, v78, v79
	v_add_f32_e32 v0, 1.0, v0
	v_rcp_f32_e32 v85, v0
	v_mul_f32_e32 v0, 0x3d372713, v74
	v_mul_f32_e32 v0, v74, v0
	v_fma_f32 v0, v74, v0, v74
	v_mul_f32_e32 v0, 0x3f4c422a, v0
	v_mul_f32_e32 v0, 0x4038aa3b, v0
	v_exp_f32_e32 v0, v0
	v_pk_fma_f32 v[84:85], v[84:85], 2.0, 1.0 op_sel_hi:[1,0,0] neg_lo:[1,0,0] neg_hi:[1,0,0]
	v_add_f32_e32 v0, 1.0, v0
	v_pk_add_f32 v[84:85], v[84:85], 1.0 op_sel_hi:[1,0]
	s_nop 0
	v_pk_mul_f32 v[80:81], v[80:81], v[84:85]
	s_nop 0
	v_cvt_pk_bf16_f32 v79, v80, v81
	v_rcp_f32_e32 v80, v0
	v_mul_f32_e32 v0, 0x3d372713, v75
	v_mul_f32_e32 v0, v75, v0
	v_fma_f32 v0, v75, v0, v75
	v_mul_f32_e32 v0, 0x3f4c422a, v0
	v_mul_f32_e32 v0, 0x4038aa3b, v0
	v_exp_f32_e32 v0, v0
	v_pk_mul_f32 v[74:75], v[74:75], 0.5 op_sel_hi:[1,0]
	v_add_f32_e32 v0, 1.0, v0
	v_rcp_f32_e32 v81, v0
	v_mul_f32_e32 v0, 0x3d372713, v76
	v_mul_f32_e32 v0, v76, v0
	v_fma_f32 v0, v76, v0, v76
	v_mul_f32_e32 v0, 0x3f4c422a, v0
	v_mul_f32_e32 v0, 0x4038aa3b, v0
	v_exp_f32_e32 v0, v0
	v_pk_fma_f32 v[80:81], v[80:81], 2.0, 1.0 op_sel_hi:[1,0,0] neg_lo:[1,0,0] neg_hi:[1,0,0]
	v_add_f32_e32 v0, 1.0, v0
	v_pk_add_f32 v[80:81], v[80:81], 1.0 op_sel_hi:[1,0]
	s_nop 0
	v_pk_mul_f32 v[74:75], v[74:75], v[80:81]
	s_nop 0
	v_cvt_pk_bf16_f32 v80, v74, v75
	v_rcp_f32_e32 v74, v0
	v_mul_f32_e32 v0, 0x3d372713, v77
	v_mul_f32_e32 v0, v77, v0
	v_fma_f32 v0, v77, v0, v77
	v_mul_f32_e32 v0, 0x3f4c422a, v0
	v_mul_f32_e32 v0, 0x4038aa3b, v0
	v_exp_f32_e32 v0, v0
	v_pk_mul_f32 v[76:77], v[76:77], 0.5 op_sel_hi:[1,0]
	v_add_f32_e32 v0, 1.0, v0
	v_rcp_f32_e32 v75, v0
	v_mul_f32_e32 v0, 0x3d372713, v70
	v_mul_f32_e32 v0, v70, v0
	v_fma_f32 v0, v70, v0, v70
	v_mul_f32_e32 v0, 0x3f4c422a, v0
	v_pk_fma_f32 v[74:75], v[74:75], 2.0, 1.0 op_sel_hi:[1,0,0] neg_lo:[1,0,0] neg_hi:[1,0,0]
	v_mul_f32_e32 v0, 0x4038aa3b, v0
	v_pk_add_f32 v[74:75], v[74:75], 1.0 op_sel_hi:[1,0]
	v_exp_f32_e32 v0, v0
	v_pk_mul_f32 v[74:75], v[76:77], v[74:75]
	v_add_f32_e32 v0, 1.0, v0
	v_cvt_pk_bf16_f32 v81, v74, v75
	v_lshl_add_u64 v[74:75], v[136:137], 0, s[0:1]
	s_mov_b32 s0, 0x1ac14000
	v_add_co_u32_e32 v76, vcc, s0, v136
	s_mov_b64 s[0:1], 0x1ac16000
	s_nop 0
	v_addc_co_u32_e32 v77, vcc, 0, v137, vcc
	global_store_dwordx4 v[76:77], v[78:81], off
	v_rcp_f32_e32 v76, v0
	v_mul_f32_e32 v0, 0x3d372713, v71
	v_mul_f32_e32 v0, v71, v0
	v_fma_f32 v0, v71, v0, v71
	v_mul_f32_e32 v0, 0x3f4c422a, v0
	v_mul_f32_e32 v0, 0x4038aa3b, v0
	v_exp_f32_e32 v0, v0
	v_pk_mul_f32 v[70:71], v[70:71], 0.5 op_sel_hi:[1,0]
	v_add_f32_e32 v0, 1.0, v0
	v_rcp_f32_e32 v77, v0
	v_mul_f32_e32 v0, 0x3d372713, v72
	v_mul_f32_e32 v0, v72, v0
	v_fma_f32 v0, v72, v0, v72
	v_mul_f32_e32 v0, 0x3f4c422a, v0
	v_mul_f32_e32 v0, 0x4038aa3b, v0
	v_exp_f32_e32 v0, v0
	v_pk_fma_f32 v[76:77], v[76:77], 2.0, 1.0 op_sel_hi:[1,0,0] neg_lo:[1,0,0] neg_hi:[1,0,0]
	v_add_f32_e32 v0, 1.0, v0
	v_pk_add_f32 v[76:77], v[76:77], 1.0 op_sel_hi:[1,0]
	s_nop 0
	v_pk_mul_f32 v[70:71], v[70:71], v[76:77]
	v_rcp_f32_e32 v76, v0
	v_mul_f32_e32 v0, 0x3d372713, v73
	v_mul_f32_e32 v0, v73, v0
	v_fma_f32 v0, v73, v0, v73
	v_mul_f32_e32 v0, 0x3f4c422a, v0
	v_mul_f32_e32 v0, 0x4038aa3b, v0
	v_exp_f32_e32 v0, v0
	v_pk_mul_f32 v[72:73], v[72:73], 0.5 op_sel_hi:[1,0]
	v_cvt_pk_bf16_f32 v70, v70, v71
	v_add_f32_e32 v0, 1.0, v0
	v_rcp_f32_e32 v77, v0
	v_mul_f32_e32 v0, 0x3d372713, v66
	v_mul_f32_e32 v0, v66, v0
	v_fma_f32 v0, v66, v0, v66
	v_mul_f32_e32 v0, 0x3f4c422a, v0
	v_mul_f32_e32 v0, 0x4038aa3b, v0
	v_exp_f32_e32 v0, v0
	v_pk_fma_f32 v[76:77], v[76:77], 2.0, 1.0 op_sel_hi:[1,0,0] neg_lo:[1,0,0] neg_hi:[1,0,0]
	v_add_f32_e32 v0, 1.0, v0
	v_pk_add_f32 v[76:77], v[76:77], 1.0 op_sel_hi:[1,0]
	s_nop 0
	v_pk_mul_f32 v[72:73], v[72:73], v[76:77]
	v_lshl_add_u64 v[76:77], v[136:137], 0, s[0:1]
	v_cvt_pk_bf16_f32 v71, v72, v73
	v_rcp_f32_e32 v72, v0
	v_mul_f32_e32 v0, 0x3d372713, v67
	v_mul_f32_e32 v0, v67, v0
	v_fma_f32 v0, v67, v0, v67
	v_mul_f32_e32 v0, 0x3f4c422a, v0
	v_mul_f32_e32 v0, 0x4038aa3b, v0
	v_exp_f32_e32 v0, v0
	v_pk_mul_f32 v[66:67], v[66:67], 0.5 op_sel_hi:[1,0]
	s_mov_b32 s0, 0x1ac16000
	v_add_f32_e32 v0, 1.0, v0
	v_rcp_f32_e32 v73, v0
	v_mul_f32_e32 v0, 0x3d372713, v68
	v_mul_f32_e32 v0, v68, v0
	v_fma_f32 v0, v68, v0, v68
	v_mul_f32_e32 v0, 0x3f4c422a, v0
	v_mul_f32_e32 v0, 0x4038aa3b, v0
	v_exp_f32_e32 v0, v0
	v_pk_fma_f32 v[72:73], v[72:73], 2.0, 1.0 op_sel_hi:[1,0,0] neg_lo:[1,0,0] neg_hi:[1,0,0]
	v_add_f32_e32 v0, 1.0, v0
	v_pk_add_f32 v[72:73], v[72:73], 1.0 op_sel_hi:[1,0]
	s_nop 0
	v_pk_mul_f32 v[66:67], v[66:67], v[72:73]
	s_nop 0
	v_cvt_pk_bf16_f32 v72, v66, v67
	v_rcp_f32_e32 v66, v0
	v_mul_f32_e32 v0, 0x3d372713, v69
	v_mul_f32_e32 v0, v69, v0
	v_fma_f32 v0, v69, v0, v69
	v_mul_f32_e32 v0, 0x3f4c422a, v0
	v_mul_f32_e32 v0, 0x4038aa3b, v0
	v_exp_f32_e32 v0, v0
	v_pk_mul_f32 v[68:69], v[68:69], 0.5 op_sel_hi:[1,0]
	v_add_f32_e32 v0, 1.0, v0
	v_rcp_f32_e32 v67, v0
	s_nop 0
	v_pk_fma_f32 v[66:67], v[66:67], 2.0, 1.0 op_sel_hi:[1,0,0] neg_lo:[1,0,0] neg_hi:[1,0,0]
	s_nop 0
	v_pk_add_f32 v[66:67], v[66:67], 1.0 op_sel_hi:[1,0]
	s_nop 0
	v_pk_mul_f32 v[66:67], v[68:69], v[66:67]
	s_nop 0
	v_cvt_pk_bf16_f32 v73, v66, v67
	v_add_co_u32_e32 v66, vcc, s0, v136
	s_nop 1
	v_addc_co_u32_e32 v67, vcc, 0, v137, vcc
	global_store_dwordx4 v[66:67], v[70:73], off
	global_load_dwordx4 v[66:69], v[138:139], off offset:528
	s_nop 0
	global_load_dwordx4 v[70:73], v[138:139], off offset:512
	s_waitcnt vmcnt(1)
	v_pk_add_f32 v[58:59], v[58:59], v[66:67]
	s_waitcnt vmcnt(0)
	v_pk_add_f32 v[62:63], v[62:63], v[70:71]
	v_pk_add_f32 v[64:65], v[64:65], v[72:73]
	v_mul_f32_e32 v0, 0x3d372713, v62
	v_mul_f32_e32 v0, v62, v0
	v_fma_f32 v0, v62, v0, v62
	v_mul_f32_e32 v0, 0x3f4c422a, v0
	v_mul_f32_e32 v0, 0x4038aa3b, v0
	v_exp_f32_e32 v0, v0
	v_pk_add_f32 v[60:61], v[60:61], v[68:69]
	v_pk_add_f32 v[54:55], v[54:55], v[70:71]
	v_pk_add_f32 v[56:57], v[56:57], v[72:73]
	v_add_f32_e32 v0, 1.0, v0
	v_rcp_f32_e32 v78, v0
	v_mul_f32_e32 v0, 0x3d372713, v63
	v_mul_f32_e32 v0, v63, v0
	v_fma_f32 v0, v63, v0, v63
	v_mul_f32_e32 v0, 0x3f4c422a, v0
	v_mul_f32_e32 v0, 0x4038aa3b, v0
	v_exp_f32_e32 v0, v0
	v_pk_mul_f32 v[62:63], v[62:63], 0.5 op_sel_hi:[1,0]
	v_pk_add_f32 v[50:51], v[50:51], v[66:67]
	v_pk_add_f32 v[52:53], v[52:53], v[68:69]
	v_add_f32_e32 v0, 1.0, v0
	v_rcp_f32_e32 v79, v0
	v_mul_f32_e32 v0, 0x3d372713, v64
	v_mul_f32_e32 v0, v64, v0
	v_fma_f32 v0, v64, v0, v64
	v_mul_f32_e32 v0, 0x3f4c422a, v0
	v_mul_f32_e32 v0, 0x4038aa3b, v0
	v_exp_f32_e32 v0, v0
	v_pk_fma_f32 v[78:79], v[78:79], 2.0, 1.0 op_sel_hi:[1,0,0] neg_lo:[1,0,0] neg_hi:[1,0,0]
	v_pk_add_f32 v[46:47], v[46:47], v[70:71]
	v_pk_add_f32 v[78:79], v[78:79], 1.0 op_sel_hi:[1,0]
	v_add_f32_e32 v0, 1.0, v0
	v_pk_mul_f32 v[62:63], v[62:63], v[78:79]
	v_rcp_f32_e32 v78, v0
	v_mul_f32_e32 v0, 0x3d372713, v65
	v_mul_f32_e32 v0, v65, v0
	v_fma_f32 v0, v65, v0, v65
	v_mul_f32_e32 v0, 0x3f4c422a, v0
	v_mul_f32_e32 v0, 0x4038aa3b, v0
	v_exp_f32_e32 v0, v0
	v_pk_mul_f32 v[64:65], v[64:65], 0.5 op_sel_hi:[1,0]
	v_cvt_pk_bf16_f32 v62, v62, v63
	v_pk_add_f32 v[48:49], v[48:49], v[72:73]
	v_add_f32_e32 v0, 1.0, v0
	v_rcp_f32_e32 v79, v0
	v_mul_f32_e32 v0, 0x3d372713, v58
	v_mul_f32_e32 v0, v58, v0
	v_fma_f32 v0, v58, v0, v58
	v_mul_f32_e32 v0, 0x3f4c422a, v0
	v_mul_f32_e32 v0, 0x4038aa3b, v0
	v_exp_f32_e32 v0, v0
	v_pk_fma_f32 v[78:79], v[78:79], 2.0, 1.0 op_sel_hi:[1,0,0] neg_lo:[1,0,0] neg_hi:[1,0,0]
	v_pk_add_f32 v[42:43], v[42:43], v[66:67]
	v_pk_add_f32 v[78:79], v[78:79], 1.0 op_sel_hi:[1,0]
	v_add_f32_e32 v0, 1.0, v0
	v_pk_mul_f32 v[64:65], v[64:65], v[78:79]
	v_pk_add_f32 v[44:45], v[44:45], v[68:69]
	v_cvt_pk_bf16_f32 v63, v64, v65
	v_rcp_f32_e32 v64, v0
	v_mul_f32_e32 v0, 0x3d372713, v59
	v_mul_f32_e32 v0, v59, v0
	v_fma_f32 v0, v59, v0, v59
	v_mul_f32_e32 v0, 0x3f4c422a, v0
	v_mul_f32_e32 v0, 0x4038aa3b, v0
	v_exp_f32_e32 v0, v0
	v_pk_mul_f32 v[58:59], v[58:59], 0.5 op_sel_hi:[1,0]
	v_pk_add_f32 v[38:39], v[38:39], v[70:71]
	v_pk_add_f32 v[40:41], v[40:41], v[72:73]
	v_add_f32_e32 v0, 1.0, v0
	v_rcp_f32_e32 v65, v0
	v_mul_f32_e32 v0, 0x3d372713, v60
	v_mul_f32_e32 v0, v60, v0
	v_fma_f32 v0, v60, v0, v60
	v_mul_f32_e32 v0, 0x3f4c422a, v0
	v_mul_f32_e32 v0, 0x4038aa3b, v0
	v_exp_f32_e32 v0, v0
	v_pk_fma_f32 v[64:65], v[64:65], 2.0, 1.0 op_sel_hi:[1,0,0] neg_lo:[1,0,0] neg_hi:[1,0,0]
	v_pk_add_f32 v[34:35], v[34:35], v[66:67]
	v_pk_add_f32 v[64:65], v[64:65], 1.0 op_sel_hi:[1,0]
	v_add_f32_e32 v0, 1.0, v0
	v_pk_mul_f32 v[58:59], v[58:59], v[64:65]
	v_pk_add_f32 v[36:37], v[36:37], v[68:69]
	v_cvt_pk_bf16_f32 v64, v58, v59
	v_rcp_f32_e32 v58, v0
	v_mul_f32_e32 v0, 0x3d372713, v61
	v_mul_f32_e32 v0, v61, v0
	v_fma_f32 v0, v61, v0, v61
	v_mul_f32_e32 v0, 0x3f4c422a, v0
	v_mul_f32_e32 v0, 0x4038aa3b, v0
	v_exp_f32_e32 v0, v0
	v_pk_mul_f32 v[60:61], v[60:61], 0.5 op_sel_hi:[1,0]
	v_pk_add_f32 v[30:31], v[30:31], v[70:71]
	v_pk_add_f32 v[32:33], v[32:33], v[72:73]
	v_add_f32_e32 v0, 1.0, v0
	v_rcp_f32_e32 v59, v0
	v_mul_f32_e32 v0, 0x3d372713, v54
	v_mul_f32_e32 v0, v54, v0
	v_fma_f32 v0, v54, v0, v54
	v_mul_f32_e32 v0, 0x3f4c422a, v0
	v_mul_f32_e32 v0, 0x4038aa3b, v0
	v_exp_f32_e32 v0, v0
	v_pk_fma_f32 v[58:59], v[58:59], 2.0, 1.0 op_sel_hi:[1,0,0] neg_lo:[1,0,0] neg_hi:[1,0,0]
	v_pk_add_f32 v[26:27], v[26:27], v[66:67]
	v_pk_add_f32 v[58:59], v[58:59], 1.0 op_sel_hi:[1,0]
	v_add_f32_e32 v0, 1.0, v0
	v_pk_mul_f32 v[58:59], v[60:61], v[58:59]
	v_pk_add_f32 v[28:29], v[28:29], v[68:69]
	v_cvt_pk_bf16_f32 v65, v58, v59
	v_rcp_f32_e32 v58, v0
	v_mul_f32_e32 v0, 0x3d372713, v55
	v_mul_f32_e32 v0, v55, v0
	v_fma_f32 v0, v55, v0, v55
	v_mul_f32_e32 v0, 0x3f4c422a, v0
	v_mul_f32_e32 v0, 0x4038aa3b, v0
	v_exp_f32_e32 v0, v0
	v_pk_mul_f32 v[54:55], v[54:55], 0.5 op_sel_hi:[1,0]
	v_pk_add_f32 v[22:23], v[22:23], v[70:71]
	v_pk_add_f32 v[24:25], v[24:25], v[72:73]
	v_add_f32_e32 v0, 1.0, v0
	v_rcp_f32_e32 v59, v0
	v_mul_f32_e32 v0, 0x3d372713, v56
	v_mul_f32_e32 v0, v56, v0
	v_fma_f32 v0, v56, v0, v56
	v_mul_f32_e32 v0, 0x3f4c422a, v0
	v_mul_f32_e32 v0, 0x4038aa3b, v0
	v_exp_f32_e32 v0, v0
	v_pk_fma_f32 v[58:59], v[58:59], 2.0, 1.0 op_sel_hi:[1,0,0] neg_lo:[1,0,0] neg_hi:[1,0,0]
	v_pk_add_f32 v[18:19], v[18:19], v[66:67]
	v_pk_add_f32 v[58:59], v[58:59], 1.0 op_sel_hi:[1,0]
	v_add_f32_e32 v0, 1.0, v0
	v_pk_mul_f32 v[54:55], v[54:55], v[58:59]
	v_rcp_f32_e32 v58, v0
	v_mul_f32_e32 v0, 0x3d372713, v57
	v_mul_f32_e32 v0, v57, v0
	v_fma_f32 v0, v57, v0, v57
	v_mul_f32_e32 v0, 0x3f4c422a, v0
	v_mul_f32_e32 v0, 0x4038aa3b, v0
	v_exp_f32_e32 v0, v0
	v_pk_mul_f32 v[56:57], v[56:57], 0.5 op_sel_hi:[1,0]
	v_cvt_pk_bf16_f32 v54, v54, v55
	v_pk_add_f32 v[20:21], v[20:21], v[68:69]
	v_add_f32_e32 v0, 1.0, v0
	v_rcp_f32_e32 v59, v0
	v_mul_f32_e32 v0, 0x3d372713, v50
	v_mul_f32_e32 v0, v50, v0
	v_fma_f32 v0, v50, v0, v50
	v_mul_f32_e32 v0, 0x3f4c422a, v0
	v_mul_f32_e32 v0, 0x4038aa3b, v0
	v_exp_f32_e32 v0, v0
	v_pk_fma_f32 v[58:59], v[58:59], 2.0, 1.0 op_sel_hi:[1,0,0] neg_lo:[1,0,0] neg_hi:[1,0,0]
	v_pk_add_f32 v[14:15], v[14:15], v[70:71]
	v_pk_add_f32 v[58:59], v[58:59], 1.0 op_sel_hi:[1,0]
	v_add_f32_e32 v0, 1.0, v0
	v_pk_mul_f32 v[56:57], v[56:57], v[58:59]
	v_pk_add_f32 v[16:17], v[16:17], v[72:73]
	v_cvt_pk_bf16_f32 v55, v56, v57
	v_rcp_f32_e32 v56, v0
	v_mul_f32_e32 v0, 0x3d372713, v51
	v_mul_f32_e32 v0, v51, v0
	v_fma_f32 v0, v51, v0, v51
	v_mul_f32_e32 v0, 0x3f4c422a, v0
	v_mul_f32_e32 v0, 0x4038aa3b, v0
	v_exp_f32_e32 v0, v0
	v_pk_mul_f32 v[50:51], v[50:51], 0.5 op_sel_hi:[1,0]
	v_pk_add_f32 v[10:11], v[10:11], v[66:67]
	v_pk_add_f32 v[12:13], v[12:13], v[68:69]
	v_add_f32_e32 v0, 1.0, v0
	v_rcp_f32_e32 v57, v0
	v_mul_f32_e32 v0, 0x3d372713, v52
	v_mul_f32_e32 v0, v52, v0
	v_fma_f32 v0, v52, v0, v52
	v_mul_f32_e32 v0, 0x3f4c422a, v0
	v_mul_f32_e32 v0, 0x4038aa3b, v0
	v_exp_f32_e32 v0, v0
	v_pk_fma_f32 v[56:57], v[56:57], 2.0, 1.0 op_sel_hi:[1,0,0] neg_lo:[1,0,0] neg_hi:[1,0,0]
	v_pk_add_f32 v[6:7], v[6:7], v[70:71]
	v_pk_add_f32 v[56:57], v[56:57], 1.0 op_sel_hi:[1,0]
	v_add_f32_e32 v0, 1.0, v0
	v_pk_mul_f32 v[50:51], v[50:51], v[56:57]
	v_pk_add_f32 v[8:9], v[8:9], v[72:73]
	v_cvt_pk_bf16_f32 v56, v50, v51
	v_rcp_f32_e32 v50, v0
	v_mul_f32_e32 v0, 0x3d372713, v53
	v_mul_f32_e32 v0, v53, v0
	v_fma_f32 v0, v53, v0, v53
	v_mul_f32_e32 v0, 0x3f4c422a, v0
	v_mul_f32_e32 v0, 0x4038aa3b, v0
	v_exp_f32_e32 v0, v0
	v_pk_mul_f32 v[52:53], v[52:53], 0.5 op_sel_hi:[1,0]
	v_pk_add_f32 v[2:3], v[2:3], v[66:67]
	v_pk_add_f32 v[4:5], v[4:5], v[68:69]
	v_add_f32_e32 v0, 1.0, v0
	v_rcp_f32_e32 v51, v0
	v_mul_f32_e32 v0, 0x3d372713, v46
	v_mul_f32_e32 v0, v46, v0
	v_fma_f32 v0, v46, v0, v46
	v_mul_f32_e32 v0, 0x3f4c422a, v0
	v_mul_f32_e32 v0, 0x4038aa3b, v0
	v_exp_f32_e32 v0, v0
	v_pk_fma_f32 v[50:51], v[50:51], 2.0, 1.0 op_sel_hi:[1,0,0] neg_lo:[1,0,0] neg_hi:[1,0,0]
	global_store_dwordx4 v[134:135], v[62:65], off offset:256
	v_pk_add_f32 v[50:51], v[50:51], 1.0 op_sel_hi:[1,0]
	v_add_f32_e32 v0, 1.0, v0
	v_pk_mul_f32 v[50:51], v[52:53], v[50:51]
	s_nop 0
	v_cvt_pk_bf16_f32 v57, v50, v51
	v_rcp_f32_e32 v50, v0
	v_mul_f32_e32 v0, 0x3d372713, v47
	v_mul_f32_e32 v0, v47, v0
	v_fma_f32 v0, v47, v0, v47
	v_mul_f32_e32 v0, 0x3f4c422a, v0
	v_mul_f32_e32 v0, 0x4038aa3b, v0
	v_exp_f32_e32 v0, v0
	v_pk_mul_f32 v[46:47], v[46:47], 0.5 op_sel_hi:[1,0]
	global_store_dwordx4 v[122:123], v[54:57], off offset:256
	v_add_f32_e32 v0, 1.0, v0
	v_rcp_f32_e32 v51, v0
	v_mul_f32_e32 v0, 0x3d372713, v48
	v_mul_f32_e32 v0, v48, v0
	v_fma_f32 v0, v48, v0, v48
	v_mul_f32_e32 v0, 0x3f4c422a, v0
	v_mul_f32_e32 v0, 0x4038aa3b, v0
	v_exp_f32_e32 v0, v0
	v_pk_fma_f32 v[50:51], v[50:51], 2.0, 1.0 op_sel_hi:[1,0,0] neg_lo:[1,0,0] neg_hi:[1,0,0]
	v_add_f32_e32 v0, 1.0, v0
	v_pk_add_f32 v[50:51], v[50:51], 1.0 op_sel_hi:[1,0]
	s_nop 0
	v_pk_mul_f32 v[46:47], v[46:47], v[50:51]
	v_rcp_f32_e32 v50, v0
	v_mul_f32_e32 v0, 0x3d372713, v49
	v_mul_f32_e32 v0, v49, v0
	v_fma_f32 v0, v49, v0, v49
	v_mul_f32_e32 v0, 0x3f4c422a, v0
	v_mul_f32_e32 v0, 0x4038aa3b, v0
	v_exp_f32_e32 v0, v0
	v_pk_mul_f32 v[48:49], v[48:49], 0.5 op_sel_hi:[1,0]
	v_cvt_pk_bf16_f32 v46, v46, v47
	v_add_f32_e32 v0, 1.0, v0
	v_rcp_f32_e32 v51, v0
	v_mul_f32_e32 v0, 0x3d372713, v42
	v_mul_f32_e32 v0, v42, v0
	v_fma_f32 v0, v42, v0, v42
	v_mul_f32_e32 v0, 0x3f4c422a, v0
	v_mul_f32_e32 v0, 0x4038aa3b, v0
	v_exp_f32_e32 v0, v0
	v_pk_fma_f32 v[50:51], v[50:51], 2.0, 1.0 op_sel_hi:[1,0,0] neg_lo:[1,0,0] neg_hi:[1,0,0]
	v_add_f32_e32 v0, 1.0, v0
	v_pk_add_f32 v[50:51], v[50:51], 1.0 op_sel_hi:[1,0]
	s_nop 0
	v_pk_mul_f32 v[48:49], v[48:49], v[50:51]
	s_nop 0
	v_cvt_pk_bf16_f32 v47, v48, v49
	v_rcp_f32_e32 v48, v0
	v_mul_f32_e32 v0, 0x3d372713, v43
	v_mul_f32_e32 v0, v43, v0
	v_fma_f32 v0, v43, v0, v43
	v_mul_f32_e32 v0, 0x3f4c422a, v0
	v_mul_f32_e32 v0, 0x4038aa3b, v0
	v_exp_f32_e32 v0, v0
	v_pk_mul_f32 v[42:43], v[42:43], 0.5 op_sel_hi:[1,0]
	v_add_f32_e32 v0, 1.0, v0
	v_rcp_f32_e32 v49, v0
	v_mul_f32_e32 v0, 0x3d372713, v44
	v_mul_f32_e32 v0, v44, v0
	v_fma_f32 v0, v44, v0, v44
	v_mul_f32_e32 v0, 0x3f4c422a, v0
	v_mul_f32_e32 v0, 0x4038aa3b, v0
	v_exp_f32_e32 v0, v0
	v_pk_fma_f32 v[48:49], v[48:49], 2.0, 1.0 op_sel_hi:[1,0,0] neg_lo:[1,0,0] neg_hi:[1,0,0]
	v_add_f32_e32 v0, 1.0, v0
	v_pk_add_f32 v[48:49], v[48:49], 1.0 op_sel_hi:[1,0]
	s_nop 0
	v_pk_mul_f32 v[42:43], v[42:43], v[48:49]
	s_nop 0
	v_cvt_pk_bf16_f32 v48, v42, v43
	v_rcp_f32_e32 v42, v0
	v_mul_f32_e32 v0, 0x3d372713, v45
	v_mul_f32_e32 v0, v45, v0
	v_fma_f32 v0, v45, v0, v45
	v_mul_f32_e32 v0, 0x3f4c422a, v0
	v_mul_f32_e32 v0, 0x4038aa3b, v0
	v_exp_f32_e32 v0, v0
	v_pk_mul_f32 v[44:45], v[44:45], 0.5 op_sel_hi:[1,0]
	v_add_f32_e32 v0, 1.0, v0
	v_rcp_f32_e32 v43, v0
	v_mul_f32_e32 v0, 0x3d372713, v38
	v_mul_f32_e32 v0, v38, v0
	v_fma_f32 v0, v38, v0, v38
	v_mul_f32_e32 v0, 0x3f4c422a, v0
	v_mul_f32_e32 v0, 0x4038aa3b, v0
	v_exp_f32_e32 v0, v0
	v_pk_fma_f32 v[42:43], v[42:43], 2.0, 1.0 op_sel_hi:[1,0,0] neg_lo:[1,0,0] neg_hi:[1,0,0]
	v_add_f32_e32 v0, 1.0, v0
	v_pk_add_f32 v[42:43], v[42:43], 1.0 op_sel_hi:[1,0]
	s_nop 0
	v_pk_mul_f32 v[42:43], v[44:45], v[42:43]
	s_nop 0
	v_cvt_pk_bf16_f32 v49, v42, v43
	v_rcp_f32_e32 v42, v0
	v_mul_f32_e32 v0, 0x3d372713, v39
	v_mul_f32_e32 v0, v39, v0
	v_fma_f32 v0, v39, v0, v39
	v_mul_f32_e32 v0, 0x3f4c422a, v0
	v_mul_f32_e32 v0, 0x4038aa3b, v0
	v_exp_f32_e32 v0, v0
	v_pk_mul_f32 v[38:39], v[38:39], 0.5 op_sel_hi:[1,0]
	global_store_dwordx4 v[114:115], v[46:49], off offset:256
	v_add_f32_e32 v0, 1.0, v0
	v_rcp_f32_e32 v43, v0
	v_mul_f32_e32 v0, 0x3d372713, v40
	v_mul_f32_e32 v0, v40, v0
	v_fma_f32 v0, v40, v0, v40
	v_mul_f32_e32 v0, 0x3f4c422a, v0
	v_mul_f32_e32 v0, 0x4038aa3b, v0
	v_exp_f32_e32 v0, v0
	v_pk_fma_f32 v[42:43], v[42:43], 2.0, 1.0 op_sel_hi:[1,0,0] neg_lo:[1,0,0] neg_hi:[1,0,0]
	v_add_f32_e32 v0, 1.0, v0
	v_pk_add_f32 v[42:43], v[42:43], 1.0 op_sel_hi:[1,0]
	s_nop 0
	v_pk_mul_f32 v[38:39], v[38:39], v[42:43]
	v_rcp_f32_e32 v42, v0
	v_mul_f32_e32 v0, 0x3d372713, v41
	v_mul_f32_e32 v0, v41, v0
	v_fma_f32 v0, v41, v0, v41
	v_mul_f32_e32 v0, 0x3f4c422a, v0
	v_mul_f32_e32 v0, 0x4038aa3b, v0
	v_exp_f32_e32 v0, v0
	v_pk_mul_f32 v[40:41], v[40:41], 0.5 op_sel_hi:[1,0]
	v_cvt_pk_bf16_f32 v38, v38, v39
	v_add_f32_e32 v0, 1.0, v0
	v_rcp_f32_e32 v43, v0
	v_mul_f32_e32 v0, 0x3d372713, v34
	v_mul_f32_e32 v0, v34, v0
	v_fma_f32 v0, v34, v0, v34
	v_mul_f32_e32 v0, 0x3f4c422a, v0
	v_mul_f32_e32 v0, 0x4038aa3b, v0
	v_exp_f32_e32 v0, v0
	v_pk_fma_f32 v[42:43], v[42:43], 2.0, 1.0 op_sel_hi:[1,0,0] neg_lo:[1,0,0] neg_hi:[1,0,0]
	v_add_f32_e32 v0, 1.0, v0
	v_pk_add_f32 v[42:43], v[42:43], 1.0 op_sel_hi:[1,0]
	s_nop 0
	v_pk_mul_f32 v[40:41], v[40:41], v[42:43]
	s_nop 0
	v_cvt_pk_bf16_f32 v39, v40, v41
	v_rcp_f32_e32 v40, v0
	v_mul_f32_e32 v0, 0x3d372713, v35
	v_mul_f32_e32 v0, v35, v0
	v_fma_f32 v0, v35, v0, v35
	v_mul_f32_e32 v0, 0x3f4c422a, v0
	v_mul_f32_e32 v0, 0x4038aa3b, v0
	v_exp_f32_e32 v0, v0
	v_pk_mul_f32 v[34:35], v[34:35], 0.5 op_sel_hi:[1,0]
	v_add_f32_e32 v0, 1.0, v0
	v_rcp_f32_e32 v41, v0
	v_mul_f32_e32 v0, 0x3d372713, v36
	v_mul_f32_e32 v0, v36, v0
	v_fma_f32 v0, v36, v0, v36
	v_mul_f32_e32 v0, 0x3f4c422a, v0
	v_mul_f32_e32 v0, 0x4038aa3b, v0
	v_exp_f32_e32 v0, v0
	v_pk_fma_f32 v[40:41], v[40:41], 2.0, 1.0 op_sel_hi:[1,0,0] neg_lo:[1,0,0] neg_hi:[1,0,0]
	v_add_f32_e32 v0, 1.0, v0
	v_pk_add_f32 v[40:41], v[40:41], 1.0 op_sel_hi:[1,0]
	s_nop 0
	v_pk_mul_f32 v[34:35], v[34:35], v[40:41]
	s_nop 0
	v_cvt_pk_bf16_f32 v40, v34, v35
	v_rcp_f32_e32 v34, v0
	v_mul_f32_e32 v0, 0x3d372713, v37
	v_mul_f32_e32 v0, v37, v0
	v_fma_f32 v0, v37, v0, v37
	v_mul_f32_e32 v0, 0x3f4c422a, v0
	v_mul_f32_e32 v0, 0x4038aa3b, v0
	v_exp_f32_e32 v0, v0
	v_pk_mul_f32 v[36:37], v[36:37], 0.5 op_sel_hi:[1,0]
	v_add_f32_e32 v0, 1.0, v0
	v_rcp_f32_e32 v35, v0
	v_mul_f32_e32 v0, 0x3d372713, v30
	v_mul_f32_e32 v0, v30, v0
	v_fma_f32 v0, v30, v0, v30
	v_mul_f32_e32 v0, 0x3f4c422a, v0
	v_mul_f32_e32 v0, 0x4038aa3b, v0
	v_exp_f32_e32 v0, v0
	v_pk_fma_f32 v[34:35], v[34:35], 2.0, 1.0 op_sel_hi:[1,0,0] neg_lo:[1,0,0] neg_hi:[1,0,0]
	v_add_f32_e32 v0, 1.0, v0
	v_pk_add_f32 v[34:35], v[34:35], 1.0 op_sel_hi:[1,0]
	s_nop 0
	v_pk_mul_f32 v[34:35], v[36:37], v[34:35]
	s_nop 0
	v_cvt_pk_bf16_f32 v41, v34, v35
	v_rcp_f32_e32 v34, v0
	v_mul_f32_e32 v0, 0x3d372713, v31
	v_mul_f32_e32 v0, v31, v0
	v_fma_f32 v0, v31, v0, v31
	v_mul_f32_e32 v0, 0x3f4c422a, v0
	v_mul_f32_e32 v0, 0x4038aa3b, v0
	v_exp_f32_e32 v0, v0
	v_pk_mul_f32 v[30:31], v[30:31], 0.5 op_sel_hi:[1,0]
	global_store_dwordx4 v[106:107], v[38:41], off offset:256
	v_add_f32_e32 v0, 1.0, v0
	v_rcp_f32_e32 v35, v0
	v_mul_f32_e32 v0, 0x3d372713, v32
	v_mul_f32_e32 v0, v32, v0
	v_fma_f32 v0, v32, v0, v32
	v_mul_f32_e32 v0, 0x3f4c422a, v0
	v_mul_f32_e32 v0, 0x4038aa3b, v0
	v_exp_f32_e32 v0, v0
	v_pk_fma_f32 v[34:35], v[34:35], 2.0, 1.0 op_sel_hi:[1,0,0] neg_lo:[1,0,0] neg_hi:[1,0,0]
	v_add_f32_e32 v0, 1.0, v0
	v_pk_add_f32 v[34:35], v[34:35], 1.0 op_sel_hi:[1,0]
	s_nop 0
	v_pk_mul_f32 v[30:31], v[30:31], v[34:35]
	v_rcp_f32_e32 v34, v0
	v_mul_f32_e32 v0, 0x3d372713, v33
	v_mul_f32_e32 v0, v33, v0
	v_fma_f32 v0, v33, v0, v33
	v_mul_f32_e32 v0, 0x3f4c422a, v0
	v_mul_f32_e32 v0, 0x4038aa3b, v0
	v_exp_f32_e32 v0, v0
	v_pk_mul_f32 v[32:33], v[32:33], 0.5 op_sel_hi:[1,0]
	v_cvt_pk_bf16_f32 v30, v30, v31
	v_add_f32_e32 v0, 1.0, v0
	v_rcp_f32_e32 v35, v0
	v_mul_f32_e32 v0, 0x3d372713, v26
	v_mul_f32_e32 v0, v26, v0
	v_fma_f32 v0, v26, v0, v26
	v_mul_f32_e32 v0, 0x3f4c422a, v0
	v_mul_f32_e32 v0, 0x4038aa3b, v0
	v_exp_f32_e32 v0, v0
	v_pk_fma_f32 v[34:35], v[34:35], 2.0, 1.0 op_sel_hi:[1,0,0] neg_lo:[1,0,0] neg_hi:[1,0,0]
	v_add_f32_e32 v0, 1.0, v0
	v_pk_add_f32 v[34:35], v[34:35], 1.0 op_sel_hi:[1,0]
	s_nop 0
	v_pk_mul_f32 v[32:33], v[32:33], v[34:35]
	s_nop 0
	v_cvt_pk_bf16_f32 v31, v32, v33
	v_rcp_f32_e32 v32, v0
	v_mul_f32_e32 v0, 0x3d372713, v27
	v_mul_f32_e32 v0, v27, v0
	v_fma_f32 v0, v27, v0, v27
	v_mul_f32_e32 v0, 0x3f4c422a, v0
	v_mul_f32_e32 v0, 0x4038aa3b, v0
	v_exp_f32_e32 v0, v0
	v_pk_mul_f32 v[26:27], v[26:27], 0.5 op_sel_hi:[1,0]
	v_add_f32_e32 v0, 1.0, v0
	v_rcp_f32_e32 v33, v0
	v_mul_f32_e32 v0, 0x3d372713, v28
	v_mul_f32_e32 v0, v28, v0
	v_fma_f32 v0, v28, v0, v28
	v_mul_f32_e32 v0, 0x3f4c422a, v0
	v_mul_f32_e32 v0, 0x4038aa3b, v0
	v_exp_f32_e32 v0, v0
	v_pk_fma_f32 v[32:33], v[32:33], 2.0, 1.0 op_sel_hi:[1,0,0] neg_lo:[1,0,0] neg_hi:[1,0,0]
	v_add_f32_e32 v0, 1.0, v0
	v_pk_add_f32 v[32:33], v[32:33], 1.0 op_sel_hi:[1,0]
	s_nop 0
	v_pk_mul_f32 v[26:27], v[26:27], v[32:33]
	s_nop 0
	v_cvt_pk_bf16_f32 v32, v26, v27
	v_rcp_f32_e32 v26, v0
	v_mul_f32_e32 v0, 0x3d372713, v29
	v_mul_f32_e32 v0, v29, v0
	v_fma_f32 v0, v29, v0, v29
	v_mul_f32_e32 v0, 0x3f4c422a, v0
	v_mul_f32_e32 v0, 0x4038aa3b, v0
	v_exp_f32_e32 v0, v0
	v_pk_mul_f32 v[28:29], v[28:29], 0.5 op_sel_hi:[1,0]
	v_add_f32_e32 v0, 1.0, v0
	v_rcp_f32_e32 v27, v0
	v_mul_f32_e32 v0, 0x3d372713, v22
	v_mul_f32_e32 v0, v22, v0
	v_fma_f32 v0, v22, v0, v22
	v_mul_f32_e32 v0, 0x3f4c422a, v0
	v_mul_f32_e32 v0, 0x4038aa3b, v0
	v_exp_f32_e32 v0, v0
	v_pk_fma_f32 v[26:27], v[26:27], 2.0, 1.0 op_sel_hi:[1,0,0] neg_lo:[1,0,0] neg_hi:[1,0,0]
	v_add_f32_e32 v0, 1.0, v0
	v_pk_add_f32 v[26:27], v[26:27], 1.0 op_sel_hi:[1,0]
	s_nop 0
	v_pk_mul_f32 v[26:27], v[28:29], v[26:27]
	s_nop 0
	v_cvt_pk_bf16_f32 v33, v26, v27
	v_rcp_f32_e32 v26, v0
	v_mul_f32_e32 v0, 0x3d372713, v23
	v_mul_f32_e32 v0, v23, v0
	v_fma_f32 v0, v23, v0, v23
	v_mul_f32_e32 v0, 0x3f4c422a, v0
	v_mul_f32_e32 v0, 0x4038aa3b, v0
	v_exp_f32_e32 v0, v0
	v_pk_mul_f32 v[22:23], v[22:23], 0.5 op_sel_hi:[1,0]
	global_store_dwordx4 v[98:99], v[30:33], off offset:256
	v_add_f32_e32 v0, 1.0, v0
	v_rcp_f32_e32 v27, v0
	v_mul_f32_e32 v0, 0x3d372713, v24
	v_mul_f32_e32 v0, v24, v0
	v_fma_f32 v0, v24, v0, v24
	v_mul_f32_e32 v0, 0x3f4c422a, v0
	v_mul_f32_e32 v0, 0x4038aa3b, v0
	v_exp_f32_e32 v0, v0
	v_pk_fma_f32 v[26:27], v[26:27], 2.0, 1.0 op_sel_hi:[1,0,0] neg_lo:[1,0,0] neg_hi:[1,0,0]
	v_add_f32_e32 v0, 1.0, v0
	v_pk_add_f32 v[26:27], v[26:27], 1.0 op_sel_hi:[1,0]
	s_nop 0
	v_pk_mul_f32 v[22:23], v[22:23], v[26:27]
	v_rcp_f32_e32 v26, v0
	v_mul_f32_e32 v0, 0x3d372713, v25
	v_mul_f32_e32 v0, v25, v0
	v_fma_f32 v0, v25, v0, v25
	v_mul_f32_e32 v0, 0x3f4c422a, v0
	v_mul_f32_e32 v0, 0x4038aa3b, v0
	v_exp_f32_e32 v0, v0
	v_pk_mul_f32 v[24:25], v[24:25], 0.5 op_sel_hi:[1,0]
	v_cvt_pk_bf16_f32 v22, v22, v23
	v_add_f32_e32 v0, 1.0, v0
	v_rcp_f32_e32 v27, v0
	v_mul_f32_e32 v0, 0x3d372713, v18
	v_mul_f32_e32 v0, v18, v0
	v_fma_f32 v0, v18, v0, v18
	v_mul_f32_e32 v0, 0x3f4c422a, v0
	v_mul_f32_e32 v0, 0x4038aa3b, v0
	v_exp_f32_e32 v0, v0
	v_pk_fma_f32 v[26:27], v[26:27], 2.0, 1.0 op_sel_hi:[1,0,0] neg_lo:[1,0,0] neg_hi:[1,0,0]
	v_add_f32_e32 v0, 1.0, v0
	v_pk_add_f32 v[26:27], v[26:27], 1.0 op_sel_hi:[1,0]
	s_nop 0
	v_pk_mul_f32 v[24:25], v[24:25], v[26:27]
	s_nop 0
	v_cvt_pk_bf16_f32 v23, v24, v25
	v_rcp_f32_e32 v24, v0
	v_mul_f32_e32 v0, 0x3d372713, v19
	v_mul_f32_e32 v0, v19, v0
	v_fma_f32 v0, v19, v0, v19
	v_mul_f32_e32 v0, 0x3f4c422a, v0
	v_mul_f32_e32 v0, 0x4038aa3b, v0
	v_exp_f32_e32 v0, v0
	v_pk_mul_f32 v[18:19], v[18:19], 0.5 op_sel_hi:[1,0]
	v_add_f32_e32 v0, 1.0, v0
	v_rcp_f32_e32 v25, v0
	v_mul_f32_e32 v0, 0x3d372713, v20
	v_mul_f32_e32 v0, v20, v0
	v_fma_f32 v0, v20, v0, v20
	v_mul_f32_e32 v0, 0x3f4c422a, v0
	v_mul_f32_e32 v0, 0x4038aa3b, v0
	v_exp_f32_e32 v0, v0
	v_pk_fma_f32 v[24:25], v[24:25], 2.0, 1.0 op_sel_hi:[1,0,0] neg_lo:[1,0,0] neg_hi:[1,0,0]
	v_add_f32_e32 v0, 1.0, v0
	v_pk_add_f32 v[24:25], v[24:25], 1.0 op_sel_hi:[1,0]
	s_nop 0
	v_pk_mul_f32 v[18:19], v[18:19], v[24:25]
	s_nop 0
	v_cvt_pk_bf16_f32 v24, v18, v19
	v_rcp_f32_e32 v18, v0
	v_mul_f32_e32 v0, 0x3d372713, v21
	v_mul_f32_e32 v0, v21, v0
	v_fma_f32 v0, v21, v0, v21
	v_mul_f32_e32 v0, 0x3f4c422a, v0
	v_mul_f32_e32 v0, 0x4038aa3b, v0
	v_exp_f32_e32 v0, v0
	v_pk_mul_f32 v[20:21], v[20:21], 0.5 op_sel_hi:[1,0]
	v_add_f32_e32 v0, 1.0, v0
	v_rcp_f32_e32 v19, v0
	v_mul_f32_e32 v0, 0x3d372713, v14
	v_mul_f32_e32 v0, v14, v0
	v_fma_f32 v0, v14, v0, v14
	v_mul_f32_e32 v0, 0x3f4c422a, v0
	v_mul_f32_e32 v0, 0x4038aa3b, v0
	v_exp_f32_e32 v0, v0
	v_pk_fma_f32 v[18:19], v[18:19], 2.0, 1.0 op_sel_hi:[1,0,0] neg_lo:[1,0,0] neg_hi:[1,0,0]
	v_add_f32_e32 v0, 1.0, v0
	v_pk_add_f32 v[18:19], v[18:19], 1.0 op_sel_hi:[1,0]
	s_nop 0
	v_pk_mul_f32 v[18:19], v[20:21], v[18:19]
	s_nop 0
	v_cvt_pk_bf16_f32 v25, v18, v19
	v_rcp_f32_e32 v18, v0
	v_mul_f32_e32 v0, 0x3d372713, v15
	v_mul_f32_e32 v0, v15, v0
	v_fma_f32 v0, v15, v0, v15
	v_mul_f32_e32 v0, 0x3f4c422a, v0
	v_mul_f32_e32 v0, 0x4038aa3b, v0
	v_exp_f32_e32 v0, v0
	v_pk_mul_f32 v[14:15], v[14:15], 0.5 op_sel_hi:[1,0]
	global_store_dwordx4 v[82:83], v[22:25], off offset:256
	v_add_f32_e32 v0, 1.0, v0
	v_rcp_f32_e32 v19, v0
	v_mul_f32_e32 v0, 0x3d372713, v16
	v_mul_f32_e32 v0, v16, v0
	v_fma_f32 v0, v16, v0, v16
	v_mul_f32_e32 v0, 0x3f4c422a, v0
	v_mul_f32_e32 v0, 0x4038aa3b, v0
	v_exp_f32_e32 v0, v0
	v_pk_fma_f32 v[18:19], v[18:19], 2.0, 1.0 op_sel_hi:[1,0,0] neg_lo:[1,0,0] neg_hi:[1,0,0]
	v_add_f32_e32 v0, 1.0, v0
	v_pk_add_f32 v[18:19], v[18:19], 1.0 op_sel_hi:[1,0]
	s_nop 0
	v_pk_mul_f32 v[14:15], v[14:15], v[18:19]
	v_rcp_f32_e32 v18, v0
	v_mul_f32_e32 v0, 0x3d372713, v17
	v_mul_f32_e32 v0, v17, v0
	v_fma_f32 v0, v17, v0, v17
	v_mul_f32_e32 v0, 0x3f4c422a, v0
	v_mul_f32_e32 v0, 0x4038aa3b, v0
	v_exp_f32_e32 v0, v0
	v_pk_mul_f32 v[16:17], v[16:17], 0.5 op_sel_hi:[1,0]
	v_cvt_pk_bf16_f32 v14, v14, v15
	v_add_f32_e32 v0, 1.0, v0
	v_rcp_f32_e32 v19, v0
	v_mul_f32_e32 v0, 0x3d372713, v10
	v_mul_f32_e32 v0, v10, v0
	v_fma_f32 v0, v10, v0, v10
	v_mul_f32_e32 v0, 0x3f4c422a, v0
	v_mul_f32_e32 v0, 0x4038aa3b, v0
	v_exp_f32_e32 v0, v0
	v_pk_fma_f32 v[18:19], v[18:19], 2.0, 1.0 op_sel_hi:[1,0,0] neg_lo:[1,0,0] neg_hi:[1,0,0]
	v_add_f32_e32 v0, 1.0, v0
	v_pk_add_f32 v[18:19], v[18:19], 1.0 op_sel_hi:[1,0]
	s_nop 0
	v_pk_mul_f32 v[16:17], v[16:17], v[18:19]
	s_nop 0
	v_cvt_pk_bf16_f32 v15, v16, v17
	v_rcp_f32_e32 v16, v0
	v_mul_f32_e32 v0, 0x3d372713, v11
	v_mul_f32_e32 v0, v11, v0
	v_fma_f32 v0, v11, v0, v11
	v_mul_f32_e32 v0, 0x3f4c422a, v0
	v_mul_f32_e32 v0, 0x4038aa3b, v0
	v_exp_f32_e32 v0, v0
	v_pk_mul_f32 v[10:11], v[10:11], 0.5 op_sel_hi:[1,0]
	v_add_f32_e32 v0, 1.0, v0
	v_rcp_f32_e32 v17, v0
	v_mul_f32_e32 v0, 0x3d372713, v12
	v_mul_f32_e32 v0, v12, v0
	v_fma_f32 v0, v12, v0, v12
	v_mul_f32_e32 v0, 0x3f4c422a, v0
	v_mul_f32_e32 v0, 0x4038aa3b, v0
	v_exp_f32_e32 v0, v0
	v_pk_fma_f32 v[16:17], v[16:17], 2.0, 1.0 op_sel_hi:[1,0,0] neg_lo:[1,0,0] neg_hi:[1,0,0]
	v_add_f32_e32 v0, 1.0, v0
	v_pk_add_f32 v[16:17], v[16:17], 1.0 op_sel_hi:[1,0]
	s_nop 0
	v_pk_mul_f32 v[10:11], v[10:11], v[16:17]
	s_nop 0
	v_cvt_pk_bf16_f32 v16, v10, v11
	v_rcp_f32_e32 v10, v0
	v_mul_f32_e32 v0, 0x3d372713, v13
	v_mul_f32_e32 v0, v13, v0
	v_fma_f32 v0, v13, v0, v13
	v_mul_f32_e32 v0, 0x3f4c422a, v0
	v_mul_f32_e32 v0, 0x4038aa3b, v0
	v_exp_f32_e32 v0, v0
	v_pk_mul_f32 v[12:13], v[12:13], 0.5 op_sel_hi:[1,0]
	v_add_f32_e32 v0, 1.0, v0
	v_rcp_f32_e32 v11, v0
	v_mul_f32_e32 v0, 0x3d372713, v6
	v_mul_f32_e32 v0, v6, v0
	v_fma_f32 v0, v6, v0, v6
	v_mul_f32_e32 v0, 0x3f4c422a, v0
	v_mul_f32_e32 v0, 0x4038aa3b, v0
	v_exp_f32_e32 v0, v0
	v_pk_fma_f32 v[10:11], v[10:11], 2.0, 1.0 op_sel_hi:[1,0,0] neg_lo:[1,0,0] neg_hi:[1,0,0]
	v_add_f32_e32 v0, 1.0, v0
	v_pk_add_f32 v[10:11], v[10:11], 1.0 op_sel_hi:[1,0]
	s_nop 0
	v_pk_mul_f32 v[10:11], v[12:13], v[10:11]
	s_nop 0
	v_cvt_pk_bf16_f32 v17, v10, v11
	v_rcp_f32_e32 v10, v0
	v_mul_f32_e32 v0, 0x3d372713, v7
	v_mul_f32_e32 v0, v7, v0
	v_fma_f32 v0, v7, v0, v7
	v_mul_f32_e32 v0, 0x3f4c422a, v0
	v_mul_f32_e32 v0, 0x4038aa3b, v0
	v_exp_f32_e32 v0, v0
	v_pk_mul_f32 v[6:7], v[6:7], 0.5 op_sel_hi:[1,0]
	global_store_dwordx4 v[74:75], v[14:17], off offset:256
	v_add_f32_e32 v0, 1.0, v0
	v_rcp_f32_e32 v11, v0
	v_mul_f32_e32 v0, 0x3d372713, v8
	v_mul_f32_e32 v0, v8, v0
	v_fma_f32 v0, v8, v0, v8
	v_mul_f32_e32 v0, 0x3f4c422a, v0
	v_mul_f32_e32 v0, 0x4038aa3b, v0
	v_exp_f32_e32 v0, v0
	v_pk_fma_f32 v[10:11], v[10:11], 2.0, 1.0 op_sel_hi:[1,0,0] neg_lo:[1,0,0] neg_hi:[1,0,0]
	v_add_f32_e32 v0, 1.0, v0
	v_pk_add_f32 v[10:11], v[10:11], 1.0 op_sel_hi:[1,0]
	s_nop 0
	v_pk_mul_f32 v[6:7], v[6:7], v[10:11]
	v_rcp_f32_e32 v10, v0
	v_mul_f32_e32 v0, 0x3d372713, v9
	v_mul_f32_e32 v0, v9, v0
	v_fma_f32 v0, v9, v0, v9
	v_mul_f32_e32 v0, 0x3f4c422a, v0
	v_mul_f32_e32 v0, 0x4038aa3b, v0
	v_exp_f32_e32 v0, v0
	v_pk_mul_f32 v[8:9], v[8:9], 0.5 op_sel_hi:[1,0]
	v_cvt_pk_bf16_f32 v6, v6, v7
	v_add_f32_e32 v0, 1.0, v0
	v_rcp_f32_e32 v11, v0
	v_mul_f32_e32 v0, 0x3d372713, v2
	v_mul_f32_e32 v0, v2, v0
	v_fma_f32 v0, v2, v0, v2
	v_mul_f32_e32 v0, 0x3f4c422a, v0
	v_mul_f32_e32 v0, 0x4038aa3b, v0
	v_exp_f32_e32 v0, v0
	v_pk_fma_f32 v[10:11], v[10:11], 2.0, 1.0 op_sel_hi:[1,0,0] neg_lo:[1,0,0] neg_hi:[1,0,0]
	v_add_f32_e32 v0, 1.0, v0
	v_pk_add_f32 v[10:11], v[10:11], 1.0 op_sel_hi:[1,0]
	s_nop 0
	v_pk_mul_f32 v[8:9], v[8:9], v[10:11]
	s_nop 0
	v_cvt_pk_bf16_f32 v7, v8, v9
	v_rcp_f32_e32 v8, v0
	v_mul_f32_e32 v0, 0x3d372713, v3
	v_mul_f32_e32 v0, v3, v0
	v_fma_f32 v0, v3, v0, v3
	v_mul_f32_e32 v0, 0x3f4c422a, v0
	v_mul_f32_e32 v0, 0x4038aa3b, v0
	v_exp_f32_e32 v0, v0
	v_pk_mul_f32 v[2:3], v[2:3], 0.5 op_sel_hi:[1,0]
	v_add_f32_e32 v0, 1.0, v0
	v_rcp_f32_e32 v9, v0
	v_mul_f32_e32 v0, 0x3d372713, v4
	v_mul_f32_e32 v0, v4, v0
	v_fma_f32 v0, v4, v0, v4
	v_mul_f32_e32 v0, 0x3f4c422a, v0
	v_mul_f32_e32 v0, 0x4038aa3b, v0
	v_exp_f32_e32 v0, v0
	v_pk_fma_f32 v[8:9], v[8:9], 2.0, 1.0 op_sel_hi:[1,0,0] neg_lo:[1,0,0] neg_hi:[1,0,0]
	v_add_f32_e32 v0, 1.0, v0
	v_pk_add_f32 v[8:9], v[8:9], 1.0 op_sel_hi:[1,0]
	s_nop 0
	v_pk_mul_f32 v[2:3], v[2:3], v[8:9]
	s_nop 0
	v_cvt_pk_bf16_f32 v8, v2, v3
	v_rcp_f32_e32 v2, v0
	v_mul_f32_e32 v0, 0x3d372713, v5
	v_mul_f32_e32 v0, v5, v0
	v_fma_f32 v0, v5, v0, v5
	v_mul_f32_e32 v0, 0x3f4c422a, v0
	v_mul_f32_e32 v0, 0x4038aa3b, v0
	v_exp_f32_e32 v0, v0
	v_pk_mul_f32 v[4:5], v[4:5], 0.5 op_sel_hi:[1,0]
	v_add_f32_e32 v0, 1.0, v0
	v_rcp_f32_e32 v3, v0
	s_nop 0
	v_pk_fma_f32 v[2:3], v[2:3], 2.0, 1.0 op_sel_hi:[1,0,0] neg_lo:[1,0,0] neg_hi:[1,0,0]
	s_nop 0
	v_pk_add_f32 v[2:3], v[2:3], 1.0 op_sel_hi:[1,0]
	s_nop 0
	v_pk_mul_f32 v[2:3], v[4:5], v[2:3]
	s_nop 0
	v_cvt_pk_bf16_f32 v9, v2, v3
	global_store_dwordx4 v[76:77], v[6:9], off offset:256
	s_waitcnt vmcnt(0)
	s_barrier
	buffer_inv sc1
	s_waitcnt vmcnt(0)
	v_readlane_b32 s24, v254, 40
	v_readlane_b32 s25, v253, 42
	v_readlane_b32 s1, v253, 16
	s_nop 1
	s_and_b32 s0, s24, 7
	s_lshl_b32 s0, s0, 1
	s_bfe_u32 s2, s24, 0x10003
	s_or_b32 s0, s0, s2
	s_and_b32 s2, s24, 16
	s_or_b32 s24, s0, s2
	s_lshl_b32 s0, s24, 3
	s_add_i32 s10, s0, s1
	s_branch .Lcmp2_entry

.LBB0_1362:
	s_or_b64 exec, exec, s[0:1]
	s_lshl_b32 s0, s24, 3
	v_readlane_b32 s1, v253, 16
	s_add_i32 s10, s0, s1
	s_cmpk_gt_i32 s10, 0xff
	s_waitcnt lgkmcnt(0)
	s_barrier
	s_cbranch_scc1 .Lattn_entry
	s_branch .Lcmp1_entry
.Lcmp2_entry:
	v_readlane_b32 s2, v254, 41
	v_readlane_b32 s3, v254, 42
	s_add_u32 s0, s2, 0x1b100000
	v_lshrrev_b32_e32 v3, 5, v240
	s_addc_u32 s1, s3, 0
	v_lshlrev_b32_e32 v35, 2, v3
	s_add_u32 s2, s2, 0x1b000000
	v_lshlrev_b32_e32 v2, 5, v240
	s_movk_i32 s4, 0x307
	v_and_b32_e32 v34, 31, v240
	s_addc_u32 s3, s3, 0
	v_bitop3_b32 v36, v2, s4, v240 bitop3:0xc8
	v_lshrrev_b32_e32 v2, 4, v240
	v_add_u32_e32 v66, 8, v35
	v_add_u32_e32 v78, 24, v35
	v_add_u32_e32 v87, 27, v35
	v_readlane_b32 s4, v253, 36
	v_lshlrev_b32_e32 v0, 9, v34
	v_and_b32_e32 v38, 4, v2
	v_lshrrev_b32_e32 v2, 1, v66
	v_add_u32_e32 v68, 9, v35
	v_add_u32_e32 v70, 10, v35
	v_add_u32_e32 v72, 11, v35
	v_lshrrev_b32_e32 v8, 1, v78
	v_add_u32_e32 v81, 25, v35
	v_add_u32_e32 v84, 26, v35
	v_lshlrev_b32_e32 v14, 3, v87
	v_lshlrev_b32_e32 v15, 3, v240
	s_add_u32 s4, s4, s92
	v_readlane_b32 s5, v253, 37
	v_and_b32_e32 v40, 4, v2
	v_lshlrev_b32_e32 v5, 3, v68
	v_lshrrev_b32_e32 v2, 1, v68
	v_lshlrev_b32_e32 v7, 3, v70
	v_lshrrev_b32_e32 v4, 1, v70
	v_lshlrev_b32_e32 v9, 3, v72
	v_lshrrev_b32_e32 v6, 1, v72
	v_and_b32_e32 v42, 4, v8
	v_lshlrev_b32_e32 v11, 3, v81
	v_lshrrev_b32_e32 v8, 1, v81
	v_lshlrev_b32_e32 v13, 3, v84
	v_lshrrev_b32_e32 v10, 1, v84
	v_lshrrev_b32_e32 v12, 1, v87
	v_and_b32_e32 v16, 0x1f8, v15
	v_and_or_b32 v17, v14, 32, v34
	v_lshl_add_u64 v[14:15], s[92:93], 0, v[0:1]
	v_lshlrev_b32_e32 v0, 4, v3
	s_addc_u32 s5, s5, s93
	v_and_b32_e32 v37, 63, v240
	v_and_b32_e32 v2, 4, v2
	v_and_b32_e32 v4, 4, v4
	v_and_b32_e32 v6, 4, v6
	v_and_b32_e32 v8, 4, v8
	v_and_b32_e32 v10, 4, v10
	v_and_b32_e32 v12, 4, v12
	v_and_or_b32 v5, v5, 32, v34
	v_and_or_b32 v7, v7, 32, v34
	v_and_or_b32 v9, v9, 32, v34
	v_and_or_b32 v11, v11, 32, v34
	v_and_or_b32 v13, v13, 32, v34
	v_lshl_add_u64 v[14:15], v[14:15], 0, v[0:1]
	v_lshl_add_u64 v[46:47], s[4:5], 0, v[0:1]
	s_lshl_b32 s4, s24, 8
	v_readlane_b32 s5, v253, 38
	v_or_b32_e32 v39, 1, v35
	v_or_b32_e32 v41, 2, v35
	v_or_b32_e32 v43, 3, v35
	v_lshrrev_b32_e32 v67, 4, v66
	v_lshrrev_b32_e32 v69, 4, v68
	v_lshrrev_b32_e32 v71, 4, v70
	v_lshrrev_b32_e32 v73, 4, v72
	v_or_b32_e32 v74, 16, v35
	v_or_b32_e32 v75, 17, v35
	v_or_b32_e32 v76, 18, v35
	v_or_b32_e32 v77, 19, v35
	v_bfe_u32 v79, v78, 4, 1
	v_and_b32_e32 v80, 28, v78
	v_bfe_u32 v82, v81, 4, 1
	v_and_b32_e32 v83, 29, v81
	v_bfe_u32 v85, v84, 4, 1
	v_and_b32_e32 v86, 30, v84
	v_bfe_u32 v88, v87, 4, 1
	v_and_b32_e32 v89, 31, v87
	v_lshl_add_u64 v[44:45], s[76:77], 0, v[14:15]
	s_add_i32 s11, s5, s4
	v_lshlrev_b32_e32 v90, 4, v5
	v_lshlrev_b32_e32 v48, 1, v2
	v_lshlrev_b32_e32 v91, 4, v7
	v_lshlrev_b32_e32 v50, 1, v4
	v_lshlrev_b32_e32 v92, 4, v9
	v_lshlrev_b32_e32 v52, 1, v6
	v_lshlrev_b32_e32 v54, 1, v38
	v_lshlrev_b32_e32 v93, 4, v37
	v_lshlrev_b32_e32 v94, 4, v11
	v_lshlrev_b32_e32 v56, 1, v8
	v_lshlrev_b32_e32 v95, 4, v13
	v_lshlrev_b32_e32 v58, 1, v10
	v_lshlrev_b32_e32 v96, 4, v17
	v_lshlrev_b32_e32 v60, 1, v12
	v_lshlrev_b32_e32 v97, 1, v16
	s_branch .LBB0_1365

.LBB0_1435:
	s_waitcnt vmcnt(0)
	s_barrier
	s_and_saveexec_b64 s[0:1], s[70:71]
	s_cbranch_execz .Lcmp_pub_done
	buffer_wbl2 sc1
	s_waitcnt vmcnt(0)
	v_readlane_b32 s2, v254, 41
	v_readlane_b32 s3, v254, 42
	v_mov_b32_e32 v2, 0x28000
	v_mov_b32_e32 v3, 1
	s_nop 4
	global_atomic_add v2, v3, s[2:3]
	s_waitcnt vmcnt(0)

.Lattn_entry:
	v_readlane_b32 s100, v254, 38
	s_mov_b32 s101, 0
	s_nop 1
	s_add_i32 s100, s100, 1
	s_lshl_b32 s100, s100, 5
	s_getreg_b32 s0, hwreg(HW_REG_XCC_ID, 0, 4)
	v_writelane_b32 v255, s0, 5
	v_readlane_b32 s0, v254, 41
	v_readlane_b32 s1, v254, 42
	s_add_u32 s4, s0, 0x15600000
	s_addc_u32 s5, s1, 0
	v_writelane_b32 v255, s4, 6
	s_add_u32 s3, s0, 0x19600000
	s_mov_b32 s2, 0
	v_writelane_b32 v255, s5, 7
	v_writelane_b32 v255, s3, 8
	s_addc_u32 s3, s1, 0
	v_writelane_b32 v255, s3, 9
	s_add_u32 s3, s0, 0x1ab00000
	v_writelane_b32 v255, s3, 10
	s_addc_u32 s3, s1, 0
	v_writelane_b32 v255, s3, 11
	s_add_u32 s3, s0, 0x16600000
	v_writelane_b32 v255, s3, 12
	s_addc_u32 s3, s1, 0
	s_add_u32 s4, s0, 0x13600000
	v_writelane_b32 v255, s3, 13
	s_addc_u32 s5, s1, 0
	v_writelane_b32 v255, s4, 14
	s_add_u32 s3, s0, 0x18600000
	v_cmp_eq_u32_e64 s[6:7], 0, v240
	v_writelane_b32 v255, s5, 15
	v_writelane_b32 v255, s3, 16
	s_addc_u32 s3, s1, 0
	v_writelane_b32 v255, s3, 17
	s_add_u32 s3, s0, 0x14600000
	v_writelane_b32 v255, s3, 18
	s_addc_u32 s3, s1, 0
	v_writelane_b32 v255, s3, 19
	s_add_u32 s3, s0, 0x1aa00000
	v_writelane_b32 v255, s3, 20
	s_addc_u32 s3, s1, 0
	s_add_u32 s4, s0, 0xf400000
	s_addc_u32 s5, s1, 0
	v_writelane_b32 v254, s4, 61
	v_writelane_b32 v255, s3, 21
	s_nop 0
	v_writelane_b32 v254, s5, 62
	s_add_u32 s4, s0, 0x1a600000
	s_addc_u32 s5, s1, 0
	v_writelane_b32 v254, s4, 59
	s_add_u32 s3, s0, 0x1b000000
	s_nop 0
	v_writelane_b32 v254, s5, 60
	v_writelane_b32 v254, s3, 57
	s_addc_u32 s3, s1, 0
	v_writelane_b32 v254, s3, 55
	s_add_u32 s3, s0, 0x1b100000
	v_writelane_b32 v254, s3, 53
	s_addc_u32 s3, s1, 0
	v_writelane_b32 v254, s3, 51
	s_add_u32 s3, s0, 0x17600000
	v_writelane_b32 v255, s3, 22
	s_addc_u32 s3, s1, 0
	v_writelane_b32 v255, s3, 23
	s_add_u32 s3, s0, 0x12600000
	v_writelane_b32 v254, s3, 47
	s_addc_u32 s3, s1, 0
	v_writelane_b32 v254, s3, 49
	s_add_u32 s3, s0, 0x12e00000
	v_writelane_b32 v255, s3, 24
	s_addc_u32 s3, s1, 0
	v_writelane_b32 v255, s3, 25
	s_add_u32 s0, s0, 0x17e00000
	v_writelane_b32 v255, s0, 26
	s_addc_u32 s0, s1, 0
	v_writelane_b32 v255, s0, 27
	s_branch .LBB0_1489

.LBB0_1498:
	s_or_b64 exec, exec, s[0:1]
	v_readfirstlane_b32 s40, v0
	s_cmpk_gt_u32 s40, 0x7ff
	s_mov_b64 s[0:1], -1
	s_cbranch_scc1 .LBB0_1493
	s_xor_b32 s40, s40, 0x400
	v_mov_b32_e32 v188, v240
	s_cmpk_gt_u32 s40, 0x3ff
	v_ashrrev_i32_e32 v196, 5, v188
	s_cbranch_scc0 .LBB0_1565
	s_not_b32 s0, s40
	s_bfe_u32 s42, s0, 0x60002
	v_ashrrev_i32_e32 v189, 5, v188
	s_and_b32 s43, s40, 3
	s_lshl_b32 s41, s42, 5
	s_waitcnt vmcnt(15)
	v_lshlrev_b32_e32 v146, 3, v189
	s_cmpk_gt_u32 s40, 0x5ff
	v_and_or_b32 v190, v188, 31, s41
	v_ashrrev_i32_e32 v147, 31, v146
	s_mov_b64 s[0:1], -1
	s_cbranch_scc0 .LBB0_1541
	s_add_i32 s0, s40, 0xfffffa00
	s_lshr_b32 s0, s0, 6
	s_and_b32 s0, s0, 0x3fffffc
	v_readlane_b32 s1, v255, 1
	s_add_i32 s0, s0, s1
	s_or_b32 s36, s0, s43
	s_lshl_b32 s0, s0, 9
	s_and_b32 s0, s0, 0x7800
	v_or_b32_e32 v184, s0, v190
	v_readlane_b32 s0, v255, 6
	v_lshlrev_b32_e32 v0, 9, v184
	v_readlane_b32 s1, v255, 7
	s_mov_b32 s19, s37
	v_readlane_b32 s2, v255, 10
	v_lshl_add_u64 v[2:3], s[0:1], 0, v[0:1]
	s_lshl_b32 s0, s36, 6
	s_and_b32 s0, s0, 0xc0
	s_lshl_b32 s18, s0, 1
	v_lshl_add_u64 v[2:3], v[2:3], 0, s[18:19]
	v_lshl_add_u64 v[2:3], v[146:147], 1, v[2:3]
	global_load_dwordx4 v[66:69], v[2:3], off
	global_load_dwordx4 v[70:73], v[2:3], off offset:32
	global_load_dwordx4 v[74:77], v[2:3], off offset:64
	global_load_dwordx4 v[78:81], v[2:3], off offset:96
	s_lshl_b64 s[0:1], s[36:37], 11
	s_add_u32 s0, s2, s0
	v_readlane_b32 s2, v255, 11
	s_addc_u32 s1, s2, s1
	s_cmp_lt_u32 s42, 8
	v_lshl_add_u64 v[2:3], v[146:147], 2, s[0:1]
	s_cselect_b64 s[0:1], -1, 0
	v_mov_b32_e32 v0, 0
	v_mov_b32_e32 v16, 0
	s_and_b64 vcc, exec, s[0:1]
	s_waitcnt vmcnt(3)
	v_lshlrev_b32_e32 v29, 16, v66
	v_lshlrev_b32_e32 v30, 16, v68
	v_and_b32_e32 v31, 0xffff0000, v66
	v_and_b32_e32 v32, 0xffff0000, v68
	v_lshlrev_b32_e32 v33, 16, v67
	v_lshlrev_b32_e32 v34, 16, v69
	v_and_b32_e32 v35, 0xffff0000, v67
	v_and_b32_e32 v36, 0xffff0000, v69
	s_waitcnt vmcnt(2)
	v_lshlrev_b32_e32 v21, 16, v70
	v_lshlrev_b32_e32 v22, 16, v72
	v_and_b32_e32 v23, 0xffff0000, v70
	v_and_b32_e32 v24, 0xffff0000, v72
	v_lshlrev_b32_e32 v25, 16, v71
	v_lshlrev_b32_e32 v26, 16, v73
	v_and_b32_e32 v27, 0xffff0000, v71
	v_and_b32_e32 v28, 0xffff0000, v73
	s_waitcnt vmcnt(1)
	v_lshlrev_b32_e32 v17, 16, v74
	v_lshlrev_b32_e32 v18, 16, v76
	v_and_b32_e32 v19, 0xffff0000, v74
	v_and_b32_e32 v20, 0xffff0000, v76
	v_lshlrev_b32_e32 v15, 16, v75
	v_lshlrev_b32_e32 v14, 16, v77
	v_and_b32_e32 v13, 0xffff0000, v75
	v_and_b32_e32 v12, 0xffff0000, v77
	s_waitcnt vmcnt(0)
	v_lshlrev_b32_e32 v11, 16, v78
	v_lshlrev_b32_e32 v10, 16, v80
	v_and_b32_e32 v9, 0xffff0000, v78
	v_and_b32_e32 v8, 0xffff0000, v80
	v_lshlrev_b32_e32 v7, 16, v79
	v_lshlrev_b32_e32 v6, 16, v81
	v_and_b32_e32 v5, 0xffff0000, v79
	v_and_b32_e32 v4, 0xffff0000, v81
	s_cbranch_vccnz .LBB0_1503
	global_load_dwordx4 v[38:41], v[2:3], off offset:16
	global_load_dwordx4 v[42:45], v[2:3], off
	v_xor_b32_e32 v37, 32, v235
	s_waitcnt vmcnt(0)
	v_fma_f32 v16, v42, v29, 0
	v_fmac_f32_e32 v16, v38, v30
	v_fmac_f32_e32 v16, v43, v31
	v_fmac_f32_e32 v16, v39, v32
	v_fmac_f32_e32 v16, v44, v33
	v_fmac_f32_e32 v16, v40, v34
	v_fmac_f32_e32 v16, v45, v35
	v_fmac_f32_e32 v16, v41, v36
	global_load_dwordx4 v[38:41], v[2:3], off offset:80
	global_load_dwordx4 v[42:45], v[2:3], off offset:64
	s_waitcnt vmcnt(0)
	v_fmac_f32_e32 v16, v42, v21
	v_fmac_f32_e32 v16, v38, v22
	v_fmac_f32_e32 v16, v43, v23
	v_fmac_f32_e32 v16, v39, v24
	v_fmac_f32_e32 v16, v44, v25
	v_fmac_f32_e32 v16, v40, v26
	v_fmac_f32_e32 v16, v45, v27
	v_fmac_f32_e32 v16, v41, v28
	global_load_dwordx4 v[38:41], v[2:3], off offset:144
	global_load_dwordx4 v[42:45], v[2:3], off offset:128
	s_waitcnt vmcnt(0)
	v_fmac_f32_e32 v16, v42, v17
	v_fmac_f32_e32 v16, v38, v18
	v_fmac_f32_e32 v16, v43, v19
	v_fmac_f32_e32 v16, v39, v20
	v_mov_b32_e32 v38, v40
	v_mov_b32_e32 v39, v44
	v_pk_mul_f32 v[38:39], v[38:39], v[14:15]
	v_mov_b32_e32 v44, v41
	v_add_f32_e32 v16, v39, v16
	v_add_f32_e32 v16, v38, v16
	v_pk_mul_f32 v[38:39], v[44:45], v[12:13]
	s_nop 0
	v_add_f32_e32 v16, v39, v16
	v_add_f32_e32 v16, v38, v16
	global_load_dwordx4 v[38:41], v[2:3], off offset:208
	global_load_dwordx4 v[42:45], v[2:3], off offset:192
	s_waitcnt vmcnt(1)
	v_mov_b32_e32 v46, v38
	s_waitcnt vmcnt(0)
	v_mov_b32_e32 v47, v42
	v_pk_mul_f32 v[46:47], v[46:47], v[10:11]
	v_mov_b32_e32 v42, v39
	v_add_f32_e32 v16, v47, v16
	v_add_f32_e32 v16, v46, v16
	v_pk_mul_f32 v[38:39], v[42:43], v[8:9]
	s_nop 0
	v_add_f32_e32 v16, v39, v16
	v_add_f32_e32 v16, v38, v16
	v_mov_b32_e32 v38, v40
	v_mov_b32_e32 v39, v44
	v_pk_mul_f32 v[38:39], v[38:39], v[6:7]
	v_mov_b32_e32 v44, v41
	v_add_f32_e32 v16, v39, v16
	v_add_f32_e32 v16, v38, v16
	v_pk_mul_f32 v[38:39], v[44:45], v[4:5]
	s_nop 0
	v_add_f32_e32 v16, v39, v16
	v_add_f32_e32 v16, v38, v16
	v_and_b32_e32 v38, 64, v235
	v_add_u32_e32 v38, 64, v38
	v_cmp_lt_i32_e32 vcc, v37, v38
	s_nop 1
	v_cndmask_b32_e32 v37, v235, v37, vcc
	v_lshlrev_b32_e32 v37, 2, v37
	ds_bpermute_b32 v37, v37, v16
	s_waitcnt lgkmcnt(0)
	v_add_f32_e32 v16, v16, v37

.LBB0_1565:
	s_andn2_b64 vcc, exec, s[0:1]
	s_cbranch_vccnz .LBB0_1492
	s_cmp_lg_u32 s101, 0
	s_cbranch_scc1 .Lnsa_ready
	v_readlane_b32 s8, v254, 41
	v_readlane_b32 s9, v254, 42
	v_mov_b32_e32 v36, 0x28000
	s_nop 4
.Lnsa_poll:
	global_load_dword v37, v36, s[8:9] sc1
	s_waitcnt vmcnt(0)
	v_readfirstlane_b32 s10, v37
	s_nop 3
	s_cmp_ge_u32 s10, s100
	s_cbranch_scc1 .Lnsa_acq
	s_sleep 8
	s_branch .Lnsa_poll
.Lnsa_acq:
	buffer_inv sc1
	s_waitcnt vmcnt(0)
	s_mov_b32 s101, 1
.Lnsa_ready:
	s_lshr_b32 s2, s40, 1
	s_and_b32 s2, s2, 0xfc
	s_and_b32 s3, s40, 3
	s_or_b32 s2, s2, s3
	s_xor_b32 s86, s2, 0xfc
	s_lshr_b32 s0, s40, 9
	v_readlane_b32 s1, v254, 63
	s_lshl_b32 s89, s86, 3
	s_waitcnt vmcnt(3)
	v_bfe_u32 v129, v188, 2, 3
	s_or_b32 s0, s0, s1
	v_or_b32_e32 v197, s89, v129
	s_bfe_u32 s1, s40, 0x10002
	v_and_b32_e32 v130, 3, v188
	v_lshl_or_b32 v148, s0, 11, v197
	s_lshl_b32 s0, s0, 1
	v_lshl_or_b32 v128, s1, 2, v130
	s_or_b32 s36, s0, s1
	v_mov_b32_e32 v149, v1
	v_readlane_b32 s0, v254, 61
	v_lshlrev_b64 v[2:3], 10, v[148:149]
	v_readlane_b32 s1, v254, 62
	v_readlane_b32 s2, v254, 57
	v_lshlrev_b32_e32 v154, 3, v188
	v_lshl_add_u64 v[2:3], s[0:1], 0, v[2:3]
	s_lshl_b64 s[0:1], s[36:37], 14
	s_add_u32 s4, s2, s0
	v_readlane_b32 s2, v254, 55
	v_ashrrev_i32_e32 v155, 31, v154
	s_addc_u32 s5, s2, s1
	v_lshlrev_b64 v[152:153], 1, v[154:155]
	v_lshl_add_u64 v[42:43], s[4:5], 0, v[152:153]
	s_movk_i32 s2, 0x2000
	v_add_co_u32_e32 v46, vcc, s2, v42
	v_lshlrev_b32_e32 v0, 7, v128
	s_nop 0
	v_addc_co_u32_e32 v47, vcc, 0, v43, vcc
	v_lshl_add_u64 v[6:7], v[2:3], 0, v[0:1]
	global_load_dwordx4 v[2:5], v[46:47], off offset:-4096
	v_lshlrev_b32_e32 v8, 3, v196
	v_ashrrev_i32_e32 v9, 31, v8
	v_lshl_add_u64 v[52:53], v[8:9], 1, v[6:7]
	global_load_dwordx4 v[80:83], v[52:53], off
	global_load_dwordx4 v[18:21], v[42:43], off
	s_movk_i32 s3, 0x1000
	v_add_co_u32_e32 v50, vcc, s3, v42
	global_load_dwordx4 v[84:87], v[52:53], off offset:32
	s_nop 0
	v_addc_co_u32_e32 v51, vcc, 0, v43, vcc
	global_load_dwordx4 v[38:41], v[50:51], off offset:1024
	v_readlane_b32 s4, v254, 59
	v_readlane_b32 s5, v254, 60
	global_load_dwordx4 v[54:57], v[42:43], off offset:1024
	global_load_dwordx4 v[58:61], v[42:43], off offset:2048
	v_mov_b64_e32 v[6:7], s[4:5]
	s_movk_i32 s4, 0x60
	v_mad_u64_u32 v[6:7], s[4:5], v148, s4, v[6:7]
	v_readlane_b32 s4, v254, 53
	s_add_u32 s0, s4, s0
	v_readlane_b32 s4, v254, 51
	v_mul_u32_u24_e32 v0, 3, v128
	s_addc_u32 s1, s4, s1
	v_lshlrev_b32_e32 v0, 2, v0
	v_lshl_add_u64 v[48:49], s[0:1], 0, v[152:153]
	s_movk_i32 s0, 0x3000
	v_lshl_add_u64 v[150:151], v[6:7], 0, v[0:1]
	v_add_co_u32_e32 v44, vcc, s0, v48
	v_lshlrev_b32_e32 v66, 6, v196
	s_nop 0
	v_addc_co_u32_e32 v45, vcc, 0, v49, vcc
	global_load_dword v0, v[150:151], off
	global_load_dwordx4 v[34:37], v[44:45], off offset:3072
	global_load_dwordx4 v[88:91], v[52:53], off offset:64
	global_load_dwordx4 v[62:65], v[42:43], off offset:3072
	global_load_dwordx4 v[92:95], v[52:53], off offset:96
	v_or_b32_e32 v67, 31, v66
	v_or_b32_e32 v68, 47, v66
	v_cmp_le_i32_e32 vcc, v67, v197
	v_or_b32_e32 v69, 63, v66
	v_add_u32_e32 v70, 0x4f, v66
	v_add_u32_e32 v71, 0x9f, v66
	v_add_u32_e32 v72, 0xaf, v66
	v_add_u32_e32 v73, 0xbf, v66
	v_add_u32_e32 v74, 0xcf, v66
	v_add_u32_e32 v75, 0x19f, v66
	v_add_u32_e32 v76, 0x1af, v66
	v_lshl_add_u32 v206, v188, 2, s83
	v_cmp_eq_u32_e64 s[8:9], 0, v130
	s_waitcnt vmcnt(9)
	v_mfma_f32_32x32x16_bf16 v[18:33], v[18:21], v[80:83], 0
	v_mfma_f32_32x32x16_bf16 v[2:17], v[2:5], v[80:83], 0
	s_waitcnt vmcnt(7)
	v_mfma_f32_32x32x16_bf16 v[2:17], v[38:41], v[84:87], v[2:17]
	global_load_dwordx4 v[38:41], v[50:51], off offset:2048
	s_nop 0
	global_load_dwordx4 v[50:53], v[50:51], off offset:3072
	s_waitcnt vmcnt(8)
	v_mfma_f32_32x32x16_bf16 v[18:33], v[54:57], v[84:87], v[18:33]
	global_load_dwordx4 v[54:57], v[46:47], off
	s_waitcnt vmcnt(5)
	v_mfma_f32_32x32x16_bf16 v[18:33], v[58:61], v[88:91], v[18:33]
	v_add_u32_e32 v58, 0x11f, v66
	v_add_u32_e32 v59, 0x12f, v66
	v_add_u32_e32 v60, 0x13f, v66
	v_add_u32_e32 v61, 0x14f, v66
	s_waitcnt vmcnt(3)
	v_mfma_f32_32x32x16_bf16 v[18:33], v[62:65], v[92:95], v[18:33]
	s_waitcnt vmcnt(2)
	v_mfma_f32_32x32x16_bf16 v[2:17], v[38:41], v[88:91], v[2:17]
	s_nop 9
	v_mul_f32_e32 v18, 0x3e38aa3b, v18
	v_mul_f32_e32 v19, 0x3e38aa3b, v19
	v_cndmask_b32_e32 v62, v239, v18, vcc
	v_cmp_le_i32_e32 vcc, v68, v197
	v_mul_f32_e32 v20, 0x3e38aa3b, v20
	v_mul_f32_e32 v21, 0x3e38aa3b, v21
	v_cndmask_b32_e32 v63, v239, v19, vcc
	v_cmp_le_i32_e32 vcc, v69, v197
	v_mul_f32_e32 v22, 0x3e38aa3b, v22
	v_mul_f32_e32 v23, 0x3e38aa3b, v23
	v_cndmask_b32_e32 v64, v239, v20, vcc
	v_cmp_le_i32_e32 vcc, v70, v197
	v_mul_f32_e32 v24, 0x3e38aa3b, v24
	v_mul_f32_e32 v25, 0x3e38aa3b, v25
	v_cndmask_b32_e32 v65, v239, v21, vcc
	v_cmp_le_i32_e32 vcc, v71, v197
	v_mul_f32_e32 v26, 0x3e38aa3b, v26
	v_mul_f32_e32 v27, 0x3e38aa3b, v27
	v_cndmask_b32_e32 v67, v239, v22, vcc
	v_cmp_le_i32_e32 vcc, v72, v197
	v_mul_f32_e32 v28, 0x3e38aa3b, v28
	global_load_dwordx4 v[38:41], v[46:47], off offset:2048
	v_cndmask_b32_e32 v68, v239, v23, vcc
	v_cmp_le_i32_e32 vcc, v73, v197
	s_waitcnt vmcnt(2)
	v_mfma_f32_32x32x16_bf16 v[2:17], v[50:53], v[92:95], v[2:17]
	v_mul_f32_e32 v29, 0x3e38aa3b, v29
	v_cndmask_b32_e32 v69, v239, v24, vcc
	v_cmp_le_i32_e32 vcc, v74, v197
	v_mul_f32_e32 v30, 0x3e38aa3b, v30
	v_mul_f32_e32 v31, 0x3e38aa3b, v31
	v_cndmask_b32_e32 v70, v239, v25, vcc
	v_cmp_le_i32_e32 vcc, v58, v197
	v_add_u32_e32 v19, 0x1bf, v66
	global_load_dwordx4 v[50:53], v[46:47], off offset:3072
	v_cndmask_b32_e32 v71, v239, v26, vcc
	v_cmp_le_i32_e32 vcc, v59, v197
	v_mul_f32_e32 v20, 0x3e38aa3b, v32
	v_mul_f32_e32 v2, 0x3e38aa3b, v2
	v_cndmask_b32_e32 v72, v239, v27, vcc
	v_cmp_le_i32_e32 vcc, v60, v197
	v_max3_f32 v18, v62, s69, v63
	v_max3_f32 v18, v18, v64, v65
	v_cndmask_b32_e32 v73, v239, v28, vcc
	v_cmp_le_i32_e32 vcc, v61, v197
	global_load_dwordx4 v[58:61], v[46:47], off offset:1024
	v_mul_f32_e32 v3, 0x3e38aa3b, v3
	v_cndmask_b32_e32 v74, v239, v29, vcc
	v_cmp_le_i32_e32 vcc, v75, v197
	v_max3_f32 v18, v18, v67, v68
	v_max3_f32 v18, v18, v69, v70
	v_cndmask_b32_e32 v75, v239, v30, vcc
	v_cmp_le_i32_e32 vcc, v76, v197
	v_mul_f32_e32 v4, 0x3e38aa3b, v4
	v_max3_f32 v18, v18, v71, v72
	v_cndmask_b32_e32 v76, v239, v31, vcc
	v_cmp_le_i32_e32 vcc, v19, v197
	v_add_u32_e32 v19, 0x1cf, v66
	v_max3_f32 v18, v18, v73, v74
	v_cndmask_b32_e32 v77, v239, v20, vcc
	v_mul_f32_e32 v20, 0x3e38aa3b, v33
	v_cmp_le_i32_e32 vcc, v19, v197
	v_add_u32_e32 v19, 0x21f, v66
	v_max3_f32 v18, v18, v75, v76
	v_cndmask_b32_e32 v78, v239, v20, vcc
	v_cmp_le_i32_e32 vcc, v19, v197
	v_max3_f32 v18, v18, v77, v78
	s_nop 0
	v_cndmask_b32_e32 v46, v239, v2, vcc
	v_add_u32_e32 v2, 0x22f, v66
	v_cmp_le_i32_e32 vcc, v2, v197
	s_nop 1
	v_cndmask_b32_e32 v47, v239, v3, vcc
	v_add_u32_e32 v3, 0x23f, v66
	v_cmp_le_i32_e32 vcc, v3, v197
	v_add_u32_e32 v3, 0x24f, v66
	v_max3_f32 v2, v18, v46, v47
	v_cndmask_b32_e32 v96, v239, v4, vcc
	v_mul_f32_e32 v4, 0x3e38aa3b, v5
	v_cmp_le_i32_e32 vcc, v3, v197
	v_add_u32_e32 v3, 0x29f, v66
	s_waitcnt vmcnt(3)
	v_mfma_f32_32x32x16_bf16 v[18:33], v[54:57], v[80:83], 0
	v_cndmask_b32_e32 v97, v239, v4, vcc
	v_mul_f32_e32 v4, 0x3e38aa3b, v6
	v_cmp_le_i32_e32 vcc, v3, v197
	v_add_u32_e32 v3, 0x2af, v66
	v_max3_f32 v2, v2, v96, v97
	v_cndmask_b32_e32 v100, v239, v4, vcc
	v_mul_f32_e32 v4, 0x3e38aa3b, v7
	v_cmp_le_i32_e32 vcc, v3, v197
	v_add_u32_e32 v3, 0x2bf, v66
	s_waitcnt vmcnt(0)
	v_mfma_f32_32x32x16_bf16 v[18:33], v[58:61], v[84:87], v[18:33]
	v_cndmask_b32_e32 v101, v239, v4, vcc
	v_mul_f32_e32 v4, 0x3e38aa3b, v8
	v_cmp_le_i32_e32 vcc, v3, v197
	v_add_u32_e32 v3, 0x2cf, v66
	v_max3_f32 v2, v2, v100, v101
	v_cndmask_b32_e32 v102, v239, v4, vcc
	v_mul_f32_e32 v4, 0x3e38aa3b, v9
	v_cmp_le_i32_e32 vcc, v3, v197
	v_add_u32_e32 v3, 0x31f, v66
	v_mfma_f32_32x32x16_bf16 v[18:33], v[38:41], v[88:91], v[18:33]
	v_cndmask_b32_e32 v103, v239, v4, vcc
	v_mul_f32_e32 v4, 0x3e38aa3b, v10
	v_cmp_le_i32_e32 vcc, v3, v197
	v_add_u32_e32 v3, 0x32f, v66
	v_max3_f32 v2, v2, v102, v103
	v_cndmask_b32_e32 v104, v239, v4, vcc
	v_mul_f32_e32 v4, 0x3e38aa3b, v11
	v_cmp_le_i32_e32 vcc, v3, v197
	v_mul_f32_e32 v3, 0x3e38aa3b, v12
	v_mfma_f32_32x32x16_bf16 v[18:33], v[50:53], v[92:95], v[18:33]
	v_cndmask_b32_e32 v105, v239, v4, vcc
	v_max3_f32 v8, v2, v104, v105
	v_add_u32_e32 v2, 0x33f, v66
	v_cmp_le_i32_e32 vcc, v2, v197
	v_add_u32_e32 v2, 0x34f, v66
	v_add_u32_e32 v9, 0x39f, v66
	v_cndmask_b32_e32 v106, v239, v3, vcc
	v_mul_f32_e32 v3, 0x3e38aa3b, v13
	v_cmp_le_i32_e32 vcc, v2, v197
	v_mul_f32_e32 v10, 0x3e38aa3b, v14
	s_nop 1
	v_mul_f32_e32 v29, 0x3e38aa3b, v29
	v_cndmask_b32_e32 v107, v239, v3, vcc
	v_add_co_u32_e32 v6, vcc, s0, v42
	v_max3_f32 v8, v8, v106, v107
	s_nop 0
	v_addc_co_u32_e32 v7, vcc, 0, v43, vcc
	global_load_dwordx4 v[2:5], v[6:7], off
	global_load_dwordx4 v[54:57], v[6:7], off offset:1024
	global_load_dwordx4 v[58:61], v[6:7], off offset:2048
	global_load_dwordx4 v[38:41], v[6:7], off offset:3072
	v_cmp_le_i32_e32 vcc, v9, v197
	v_add_u32_e32 v9, 0x3af, v66
	v_add_u32_e32 v7, 0x41f, v66
	v_cndmask_b32_e32 v108, v239, v10, vcc
	v_mul_f32_e32 v10, 0x3e38aa3b, v15
	v_cmp_le_i32_e32 vcc, v9, v197
	v_add_u32_e32 v9, 0x3bf, v66
	v_mul_f32_e32 v30, 0x3e38aa3b, v30
	v_cndmask_b32_e32 v109, v239, v10, vcc
	v_mul_f32_e32 v10, 0x3e38aa3b, v16
	v_cmp_le_i32_e32 vcc, v9, v197
	v_add_u32_e32 v9, 0x3cf, v66
	v_max3_f32 v8, v8, v108, v109
	v_cndmask_b32_e32 v110, v239, v10, vcc
	v_mul_f32_e32 v10, 0x3e38aa3b, v17
	v_cmp_le_i32_e32 vcc, v9, v197
	v_mul_f32_e32 v31, 0x3e38aa3b, v31
	v_mul_f32_e32 v32, 0x3e38aa3b, v32
	v_cndmask_b32_e32 v111, v239, v10, vcc
	v_max3_f32 v6, v8, v110, v111
	v_mul_f32_e32 v8, 0x3e38aa3b, v18
	v_cmp_le_i32_e32 vcc, v7, v197
	v_add_u32_e32 v7, 0x42f, v66
	v_mul_f32_e32 v33, 0x3e38aa3b, v33
	v_cndmask_b32_e32 v50, v239, v8, vcc
	v_mul_f32_e32 v8, 0x3e38aa3b, v19
	v_cmp_le_i32_e32 vcc, v7, v197
	v_add_u32_e32 v7, 0x43f, v66
	v_add_u32_e32 v19, 0x54f, v66
	v_cndmask_b32_e32 v51, v239, v8, vcc
	v_mul_f32_e32 v8, 0x3e38aa3b, v20
	v_cmp_le_i32_e32 vcc, v7, v197
	v_add_u32_e32 v7, 0x44f, v66
	v_max3_f32 v6, v6, v50, v51
	v_cndmask_b32_e32 v20, v239, v8, vcc
	v_mul_f32_e32 v8, 0x3e38aa3b, v21
	v_cmp_le_i32_e32 vcc, v7, v197
	v_add_u32_e32 v7, 0x49f, v66
	s_nop 0
	v_cndmask_b32_e32 v21, v239, v8, vcc
	v_mul_f32_e32 v8, 0x3e38aa3b, v22
	v_cmp_le_i32_e32 vcc, v7, v197
	v_add_u32_e32 v7, 0x4af, v66
	v_max3_f32 v6, v6, v20, v21
	v_cndmask_b32_e32 v22, v239, v8, vcc
	v_mul_f32_e32 v8, 0x3e38aa3b, v23
	v_cmp_le_i32_e32 vcc, v7, v197
	v_add_u32_e32 v7, 0x4bf, v66
	s_nop 0
	v_cndmask_b32_e32 v23, v239, v8, vcc
	v_mul_f32_e32 v8, 0x3e38aa3b, v24
	v_cmp_le_i32_e32 vcc, v7, v197
	v_add_u32_e32 v7, 0x4cf, v66
	v_max3_f32 v6, v6, v22, v23
	v_cndmask_b32_e32 v24, v239, v8, vcc
	v_mul_f32_e32 v8, 0x3e38aa3b, v25
	v_cmp_le_i32_e32 vcc, v7, v197
	v_add_u32_e32 v7, 0x51f, v66
	s_nop 0
	v_cndmask_b32_e32 v25, v239, v8, vcc
	v_mul_f32_e32 v8, 0x3e38aa3b, v26
	v_cmp_le_i32_e32 vcc, v7, v197
	v_add_u32_e32 v7, 0x52f, v66
	v_max3_f32 v6, v6, v24, v25
	v_cndmask_b32_e32 v26, v239, v8, vcc
	v_mul_f32_e32 v8, 0x3e38aa3b, v27
	v_cmp_le_i32_e32 vcc, v7, v197
	v_mul_f32_e32 v7, 0x3e38aa3b, v28
	s_nop 0
	v_cndmask_b32_e32 v27, v239, v8, vcc
	v_max3_f32 v18, v6, v26, v27
	v_add_u32_e32 v6, 0x53f, v66
	v_cmp_le_i32_e32 vcc, v6, v197
	s_nop 1
	v_cndmask_b32_e32 v28, v239, v7, vcc
	s_waitcnt vmcnt(3)
	v_mfma_f32_32x32x16_bf16 v[2:17], v[2:5], v[80:83], 0
	v_cmp_le_i32_e32 vcc, v19, v197
	v_add_u32_e32 v19, 0x59f, v66
	s_nop 0
	v_cndmask_b32_e32 v29, v239, v29, vcc
	v_cmp_le_i32_e32 vcc, v19, v197
	v_add_u32_e32 v19, 0x5af, v66
	v_max3_f32 v18, v18, v28, v29
	s_waitcnt vmcnt(2)
	v_mfma_f32_32x32x16_bf16 v[2:17], v[54:57], v[84:87], v[2:17]
	v_cndmask_b32_e32 v30, v239, v30, vcc
	v_cmp_le_i32_e32 vcc, v19, v197
	v_add_u32_e32 v19, 0x5bf, v66
	s_nop 0
	v_cndmask_b32_e32 v31, v239, v31, vcc
	v_cmp_le_i32_e32 vcc, v19, v197
	v_add_u32_e32 v19, 0x5cf, v66
	s_waitcnt vmcnt(1)
	v_mfma_f32_32x32x16_bf16 v[2:17], v[58:61], v[88:91], v[2:17]
	v_cndmask_b32_e32 v32, v239, v32, vcc
	v_cmp_le_i32_e32 vcc, v19, v197
	v_add_u32_e32 v19, 0x61f, v66
	v_max3_f32 v18, v18, v30, v31
	v_cndmask_b32_e32 v33, v239, v33, vcc
	v_cmp_le_i32_e32 vcc, v19, v197
	v_max3_f32 v18, v18, v32, v33
	s_waitcnt vmcnt(0)
	v_mfma_f32_32x32x16_bf16 v[2:17], v[38:41], v[92:95], v[2:17]
	s_nop 11
	v_mul_f32_e32 v2, 0x3e38aa3b, v2
	v_cndmask_b32_e32 v114, v239, v2, vcc
	v_add_u32_e32 v2, 0x62f, v66
	v_mul_f32_e32 v3, 0x3e38aa3b, v3
	v_cmp_le_i32_e32 vcc, v2, v197
	v_mul_f32_e32 v4, 0x3e38aa3b, v4
	s_nop 0
	v_cndmask_b32_e32 v115, v239, v3, vcc
	v_add_u32_e32 v3, 0x63f, v66
	v_cmp_le_i32_e32 vcc, v3, v197
	v_add_u32_e32 v3, 0x64f, v66
	v_max3_f32 v2, v18, v114, v115
	v_cndmask_b32_e32 v116, v239, v4, vcc
	v_mul_f32_e32 v4, 0x3e38aa3b, v5
	v_cmp_le_i32_e32 vcc, v3, v197
	v_add_u32_e32 v3, 0x69f, v66
	s_nop 0
	v_cndmask_b32_e32 v117, v239, v4, vcc
	v_mul_f32_e32 v4, 0x3e38aa3b, v6
	v_cmp_le_i32_e32 vcc, v3, v197
	v_add_u32_e32 v3, 0x6af, v66
	v_max3_f32 v2, v2, v116, v117
	v_cndmask_b32_e32 v120, v239, v4, vcc
	v_mul_f32_e32 v4, 0x3e38aa3b, v7
	v_cmp_le_i32_e32 vcc, v3, v197
	v_add_u32_e32 v3, 0x6bf, v66
	s_nop 0
	v_cndmask_b32_e32 v121, v239, v4, vcc
	v_mul_f32_e32 v4, 0x3e38aa3b, v8
	v_cmp_le_i32_e32 vcc, v3, v197
	v_add_u32_e32 v3, 0x6cf, v66
	v_max3_f32 v2, v2, v120, v121
	v_cndmask_b32_e32 v122, v239, v4, vcc
	v_mul_f32_e32 v4, 0x3e38aa3b, v9
	v_cmp_le_i32_e32 vcc, v3, v197
	v_add_u32_e32 v3, 0x71f, v66
	s_nop 0
	v_cndmask_b32_e32 v123, v239, v4, vcc
	v_mul_f32_e32 v4, 0x3e38aa3b, v10
	v_cmp_le_i32_e32 vcc, v3, v197
	v_add_u32_e32 v3, 0x72f, v66
	v_max3_f32 v2, v2, v122, v123
	v_cndmask_b32_e32 v132, v239, v4, vcc
	v_mul_f32_e32 v4, 0x3e38aa3b, v11
	v_cmp_le_i32_e32 vcc, v3, v197
	v_add_u32_e32 v3, 0x73f, v66
	s_nop 0
	v_cndmask_b32_e32 v133, v239, v4, vcc
	v_mul_f32_e32 v4, 0x3e38aa3b, v12
	v_cmp_le_i32_e32 vcc, v3, v197
	v_add_u32_e32 v3, 0x74f, v66
	v_max3_f32 v2, v2, v132, v133
	v_cndmask_b32_e32 v134, v239, v4, vcc
	v_mul_f32_e32 v4, 0x3e38aa3b, v13
	v_cmp_le_i32_e32 vcc, v3, v197
	v_add_u32_e32 v3, 0x79f, v66
	s_nop 0
	v_cndmask_b32_e32 v135, v239, v4, vcc
	v_mul_f32_e32 v4, 0x3e38aa3b, v14
	v_cmp_le_i32_e32 vcc, v3, v197
	v_add_u32_e32 v3, 0x7af, v66
	v_max3_f32 v2, v2, v134, v135
	v_cndmask_b32_e32 v14, v239, v4, vcc
	v_mul_f32_e32 v4, 0x3e38aa3b, v15
	v_cmp_le_i32_e32 vcc, v3, v197
	v_add_u32_e32 v3, 0x7bf, v66
	s_nop 0
	v_cndmask_b32_e32 v15, v239, v4, vcc
	v_mul_f32_e32 v4, 0x3e38aa3b, v16
	v_cmp_le_i32_e32 vcc, v3, v197
	v_add_u32_e32 v3, 0x7cf, v66
	v_max3_f32 v2, v2, v14, v15
	v_cndmask_b32_e32 v16, v239, v4, vcc
	v_mul_f32_e32 v4, 0x3e38aa3b, v17
	v_cmp_le_i32_e32 vcc, v3, v197
	v_xor_b32_e32 v3, 32, v235
	s_nop 0
	v_cndmask_b32_e32 v17, v239, v4, vcc
	v_and_b32_e32 v4, 64, v235
	v_add_u32_e32 v131, 64, v4
	v_cmp_lt_i32_e32 vcc, v3, v131
	v_max3_f32 v2, v2, v16, v17
	s_nop 0
	v_cndmask_b32_e32 v3, v235, v3, vcc
	v_lshlrev_b32_e32 v205, 2, v3
	ds_bpermute_b32 v3, v205, v2
	s_waitcnt lgkmcnt(0)
	v_max_f32_e32 v3, v3, v3
	v_max_f32_e32 v2, v2, v3
	v_cmp_neq_f32_e32 vcc, s69, v2
	s_nop 1
	v_cndmask_b32_e32 v136, 0, v2, vcc
	v_sub_f32_e32 v2, v62, v136
	v_exp_f32_e32 v2, v2
	v_sub_f32_e32 v3, v63, v136
	v_exp_f32_e32 v3, v3
	v_sub_f32_e32 v4, v64, v136
	v_exp_f32_e32 v4, v4
	v_sub_f32_e32 v5, v65, v136
	v_exp_f32_e32 v5, v5
	v_add_f32_e32 v6, 0, v2
	v_add_f32_e32 v6, v3, v6
	v_add_f32_e32 v6, v4, v6
	v_add_f32_e32 v10, v5, v6
	v_sub_f32_e32 v6, v67, v136
	v_exp_f32_e32 v6, v6
	v_sub_f32_e32 v7, v68, v136
	v_exp_f32_e32 v7, v7
	v_sub_f32_e32 v8, v69, v136
	v_exp_f32_e32 v8, v8
	v_sub_f32_e32 v9, v70, v136
	v_exp_f32_e32 v9, v9
	v_sub_f32_e32 v11, v71, v136
	v_add_f32_e32 v10, v6, v10
	v_exp_f32_e32 v18, v11
	v_sub_f32_e32 v11, v72, v136
	v_add_f32_e32 v10, v7, v10
	v_exp_f32_e32 v19, v11
	v_sub_f32_e32 v11, v73, v136
	v_add_f32_e32 v10, v8, v10
	v_exp_f32_e32 v38, v11
	v_sub_f32_e32 v11, v74, v136
	v_add_f32_e32 v10, v9, v10
	v_exp_f32_e32 v39, v11
	v_sub_f32_e32 v11, v75, v136
	v_add_f32_e32 v10, v18, v10
	v_exp_f32_e32 v58, v11
	v_sub_f32_e32 v11, v76, v136
	v_add_f32_e32 v10, v19, v10
	v_exp_f32_e32 v59, v11
	v_sub_f32_e32 v11, v77, v136
	v_add_f32_e32 v10, v38, v10
	v_exp_f32_e32 v60, v11
	v_sub_f32_e32 v11, v78, v136
	v_add_f32_e32 v10, v39, v10
	v_exp_f32_e32 v61, v11
	v_sub_f32_e32 v11, v46, v136
	v_add_f32_e32 v10, v58, v10
	v_exp_f32_e32 v78, v11
	v_sub_f32_e32 v11, v47, v136
	v_add_f32_e32 v10, v59, v10
	v_exp_f32_e32 v79, v11
	v_sub_f32_e32 v11, v96, v136
	v_add_f32_e32 v10, v60, v10
	v_exp_f32_e32 v98, v11
	v_sub_f32_e32 v11, v97, v136
	v_add_f32_e32 v10, v61, v10
	v_exp_f32_e32 v99, v11
	v_sub_f32_e32 v11, v100, v136
	v_add_f32_e32 v10, v78, v10
	v_exp_f32_e32 v126, v11
	v_sub_f32_e32 v11, v101, v136
	v_add_f32_e32 v10, v79, v10
	v_exp_f32_e32 v127, v11
	v_sub_f32_e32 v11, v102, v136
	v_add_f32_e32 v10, v98, v10
	v_exp_f32_e32 v62, v11
	v_sub_f32_e32 v11, v103, v136
	v_add_f32_e32 v10, v99, v10
	v_exp_f32_e32 v63, v11
	v_sub_f32_e32 v11, v104, v136
	v_add_f32_e32 v10, v126, v10
	v_exp_f32_e32 v42, v11
	v_sub_f32_e32 v11, v105, v136
	v_add_f32_e32 v10, v127, v10
	v_exp_f32_e32 v43, v11
	v_sub_f32_e32 v11, v106, v136
	v_add_f32_e32 v10, v62, v10
	v_exp_f32_e32 v54, v11
	v_sub_f32_e32 v11, v107, v136
	v_add_f32_e32 v10, v63, v10
	v_exp_f32_e32 v55, v11
	v_sub_f32_e32 v11, v108, v136
	v_add_f32_e32 v10, v42, v10
	v_exp_f32_e32 v96, v11
	v_sub_f32_e32 v11, v109, v136
	v_add_f32_e32 v10, v43, v10
	v_exp_f32_e32 v97, v11
	v_sub_f32_e32 v11, v110, v136
	v_add_f32_e32 v10, v54, v10
	v_exp_f32_e32 v124, v11
	v_sub_f32_e32 v11, v111, v136
	v_add_f32_e32 v10, v55, v10
	v_exp_f32_e32 v125, v11
	v_sub_f32_e32 v11, v50, v136
	v_add_f32_e32 v10, v96, v10
	v_exp_f32_e32 v50, v11
	v_sub_f32_e32 v11, v51, v136
	v_add_f32_e32 v10, v97, v10
	v_exp_f32_e32 v51, v11
	v_sub_f32_e32 v11, v20, v136
	v_add_f32_e32 v10, v124, v10
	v_exp_f32_e32 v76, v11
	v_sub_f32_e32 v11, v21, v136
	v_add_f32_e32 v10, v125, v10
	v_exp_f32_e32 v77, v11
	v_sub_f32_e32 v11, v22, v136
	v_add_f32_e32 v10, v50, v10
	v_exp_f32_e32 v52, v11
	v_sub_f32_e32 v11, v23, v136
	v_add_f32_e32 v10, v51, v10
	v_exp_f32_e32 v53, v11
	v_sub_f32_e32 v11, v24, v136
	v_add_f32_e32 v10, v76, v10
	v_exp_f32_e32 v56, v11
	v_sub_f32_e32 v11, v25, v136
	v_add_f32_e32 v10, v77, v10
	v_exp_f32_e32 v57, v11
	v_sub_f32_e32 v11, v26, v136
	v_add_f32_e32 v10, v52, v10
	v_exp_f32_e32 v40, v11
	v_sub_f32_e32 v11, v27, v136
	v_add_f32_e32 v10, v53, v10
	v_exp_f32_e32 v41, v11
	v_sub_f32_e32 v11, v28, v136
	v_add_f32_e32 v10, v56, v10
	v_exp_f32_e32 v46, v11
	v_sub_f32_e32 v11, v29, v136
	v_add_f32_e32 v10, v57, v10
	v_exp_f32_e32 v47, v11
	v_sub_f32_e32 v11, v30, v136
	v_add_f32_e32 v10, v40, v10
	v_exp_f32_e32 v112, v11
	v_sub_f32_e32 v11, v31, v136
	v_add_f32_e32 v10, v41, v10
	v_exp_f32_e32 v113, v11
	v_sub_f32_e32 v11, v32, v136
	v_add_f32_e32 v10, v46, v10
	v_exp_f32_e32 v118, v11
	v_sub_f32_e32 v11, v33, v136
	v_add_f32_e32 v10, v47, v10
	v_exp_f32_e32 v119, v11
	v_add_f32_e32 v10, v112, v10
	v_add_f32_e32 v10, v113, v10
	v_add_f32_e32 v10, v118, v10
	v_add_f32_e32 v20, v119, v10
	v_sub_f32_e32 v10, v114, v136
	v_exp_f32_e32 v64, v10
	v_sub_f32_e32 v10, v115, v136
	v_sub_f32_e32 v21, v116, v136
	v_exp_f32_e32 v65, v10
	global_load_dwordx4 v[10:13], v[48:49], off
	v_exp_f32_e32 v72, v21
	v_sub_f32_e32 v21, v117, v136
	v_exp_f32_e32 v73, v21
	v_sub_f32_e32 v21, v120, v136
	v_exp_f32_e32 v66, v21
	v_sub_f32_e32 v21, v121, v136
	v_exp_f32_e32 v67, v21
	v_sub_f32_e32 v21, v122, v136
	v_exp_f32_e32 v74, v21
	v_sub_f32_e32 v21, v123, v136
	v_exp_f32_e32 v75, v21
	v_sub_f32_e32 v21, v132, v136
	v_exp_f32_e32 v68, v21
	v_sub_f32_e32 v21, v133, v136
	v_exp_f32_e32 v69, v21
	v_sub_f32_e32 v21, v134, v136
	v_exp_f32_e32 v70, v21
	v_sub_f32_e32 v21, v135, v136
	global_load_dwordx4 v[132:135], v[48:49], off offset:2048
	v_add_f32_e32 v20, v64, v20
	v_add_f32_e32 v20, v65, v20
	v_add_f32_e32 v20, v72, v20
	v_add_f32_e32 v20, v73, v20
	v_add_f32_e32 v20, v66, v20
	v_add_f32_e32 v20, v67, v20
	v_add_f32_e32 v20, v74, v20
	v_add_f32_e32 v20, v75, v20
	v_exp_f32_e32 v71, v21
	v_sub_f32_e32 v14, v14, v136
	v_add_f32_e32 v20, v68, v20
	v_exp_f32_e32 v102, v14
	v_sub_f32_e32 v14, v15, v136
	v_add_f32_e32 v20, v69, v20
	v_exp_f32_e32 v103, v14
	v_sub_f32_e32 v14, v16, v136
	v_add_f32_e32 v20, v70, v20
	v_exp_f32_e32 v106, v14
	v_sub_f32_e32 v14, v17, v136
	v_add_f32_e32 v20, v71, v20
	v_exp_f32_e32 v107, v14
	v_add_f32_e32 v14, v102, v20
	v_add_f32_e32 v14, v103, v14
	v_add_f32_e32 v14, v106, v14
	v_add_f32_e32 v14, v107, v14
	ds_bpermute_b32 v15, v205, v14
	global_load_dwordx4 v[20:23], v[48:49], off offset:1024
	global_load_dwordx4 v[136:139], v[48:49], off offset:3072
	s_waitcnt lgkmcnt(0)
	v_add_f32_e32 v14, v14, v15
	v_max_f32_e32 v14, 0xda24260, v14
	v_div_scale_f32 v15, s[0:1], v14, v14, 1.0
	v_rcp_f32_e32 v16, v15
	s_nop 0
	v_fma_f32 v17, -v15, v16, 1.0
	v_fmac_f32_e32 v16, v17, v16
	v_div_scale_f32 v17, vcc, 1.0, v14, 1.0
	v_mul_f32_e32 v24, v17, v16
	v_fma_f32 v25, -v15, v24, v17
	v_fmac_f32_e32 v24, v25, v16
	v_fma_f32 v15, -v15, v24, v17
	v_div_fmas_f32 v15, v15, v16, v24
	v_div_fixup_f32 v156, v15, v14, 1.0
	v_pk_mul_f32 v[120:121], v[2:3], v[156:157] op_sel_hi:[1,0]
	v_pk_mul_f32 v[122:123], v[4:5], v[156:157] op_sel_hi:[1,0]
	v_pk_mul_f32 v[110:111], v[6:7], v[156:157] op_sel_hi:[1,0]
	v_pk_mul_f32 v[116:117], v[8:9], v[156:157] op_sel_hi:[1,0]
	v_cvt_pk_bf16_f32 v24, v120, v121
	v_cvt_pk_bf16_f32 v25, v122, v123
	v_cvt_pk_bf16_f32 v26, v110, v111
	v_cvt_pk_bf16_f32 v27, v116, v117
	v_add_co_u32_e32 v158, vcc, s2, v48
	s_waitcnt vmcnt(3)
	v_mfma_f32_32x32x16_bf16 v[2:17], v[10:13], v[24:27], 0
	v_addc_co_u32_e32 v159, vcc, 0, v49, vcc
	v_mul_f32_e64 v108, v18, v156
	v_mul_f32_e64 v109, v19, v156
	v_mul_f32_e64 v114, v38, v156
	v_mul_f32_e64 v115, v39, v156
	v_pk_mul_f32 v[100:101], v[58:59], v[156:157] op_sel_hi:[1,0]
	v_pk_mul_f32 v[104:105], v[60:61], v[156:157] op_sel_hi:[1,0]
	v_add_co_u32_e32 v160, vcc, s3, v48
	v_cvt_pk_bf16_f32 v144, v108, v109
	v_cvt_pk_bf16_f32 v145, v114, v115
	v_cvt_pk_bf16_f32 v146, v100, v101
	v_cvt_pk_bf16_f32 v147, v104, v105
	v_addc_co_u32_e32 v161, vcc, 0, v49, vcc
	global_load_dwordx4 v[140:143], v[158:159], off offset:-4096
	s_waitcnt vmcnt(3)
	v_mfma_f32_32x32x16_bf16 v[2:17], v[132:135], v[144:147], v[2:17]
	global_load_dwordx4 v[132:135], v[160:161], off offset:1024
	v_mul_f32_e64 v58, v78, v156
	v_mul_f32_e64 v59, v79, v156
	v_mul_f32_e64 v60, v98, v156
	v_mul_f32_e64 v61, v99, v156
	v_pk_mul_f32 v[38:39], v[126:127], v[156:157] op_sel_hi:[1,0]
	v_pk_mul_f32 v[62:63], v[62:63], v[156:157] op_sel_hi:[1,0]
	v_pk_mul_f32 v[78:79], v[42:43], v[156:157] op_sel_hi:[1,0]
	v_pk_mul_f32 v[98:99], v[54:55], v[156:157] op_sel_hi:[1,0]
	s_waitcnt vmcnt(3)
	v_mfma_f32_32x32x16_bf16 v[18:33], v[20:23], v[24:27], 0
	v_mul_f32_e64 v42, v96, v156
	v_mul_f32_e64 v43, v97, v156
	v_mul_f32_e64 v48, v124, v156
	v_mul_f32_e64 v49, v125, v156
	v_cvt_pk_bf16_f32 v124, v78, v79
	v_cvt_pk_bf16_f32 v125, v98, v99
	v_cvt_pk_bf16_f32 v126, v42, v43
	v_cvt_pk_bf16_f32 v127, v48, v49
	v_pk_mul_f32 v[50:51], v[50:51], v[156:157] op_sel_hi:[1,0]
	s_waitcnt vmcnt(2)
	v_mfma_f32_32x32x16_bf16 v[18:33], v[136:139], v[144:147], v[18:33]
	v_cvt_pk_bf16_f32 v136, v58, v59
	v_cvt_pk_bf16_f32 v137, v60, v61
	v_cvt_pk_bf16_f32 v138, v38, v39
	v_cvt_pk_bf16_f32 v139, v62, v63
	global_load_dwordx4 v[144:147], v[158:159], off
	v_pk_mul_f32 v[54:55], v[76:77], v[156:157] op_sel_hi:[1,0]
	v_pk_mul_f32 v[52:53], v[52:53], v[156:157] op_sel_hi:[1,0]
	s_waitcnt vmcnt(2)
	v_mfma_f32_32x32x16_bf16 v[2:17], v[140:143], v[136:139], v[2:17]
	global_load_dwordx4 v[140:143], v[160:161], off offset:2048
	v_mul_f32_e64 v56, v56, v156
	v_mul_f32_e64 v57, v57, v156
	v_mul_f32_e64 v76, v40, v156
	v_mul_f32_e64 v77, v41, v156
	v_pk_mul_f32 v[96:97], v[46:47], v[156:157] op_sel_hi:[1,0]
	v_pk_mul_f32 v[40:41], v[112:113], v[156:157] op_sel_hi:[1,0]
	v_pk_mul_f32 v[46:47], v[118:119], v[156:157] op_sel_hi:[1,0]
	v_pk_mul_f32 v[64:65], v[64:65], v[156:157] op_sel_hi:[1,0]
	s_waitcnt vmcnt(2)
	v_mfma_f32_32x32x16_bf16 v[18:33], v[132:135], v[136:139], v[18:33]
	global_load_dwordx4 v[132:135], v[160:161], off offset:3072
	global_load_dwordx4 v[136:139], v[44:45], off
	v_mul_f32_e64 v72, v72, v156
	v_mul_f32_e64 v73, v73, v156
	v_mul_f32_e64 v66, v66, v156
	v_mul_f32_e64 v67, v67, v156
	v_pk_mul_f32 v[74:75], v[74:75], v[156:157] op_sel_hi:[1,0]
	v_pk_mul_f32 v[112:113], v[68:69], v[156:157] op_sel_hi:[1,0]
	v_pk_mul_f32 v[70:71], v[70:71], v[156:157] op_sel_hi:[1,0]
	s_waitcnt vmcnt(2)
	v_mfma_f32_32x32x16_bf16 v[2:17], v[140:143], v[124:127], v[2:17]
	global_load_dwordx4 v[140:143], v[158:159], off offset:2048
	v_mul_f32_e64 v68, v106, v156
	v_mul_f32_e64 v69, v107, v156
	s_waitcnt vmcnt(2)
	v_mfma_f32_32x32x16_bf16 v[18:33], v[132:135], v[124:127], v[18:33]
	global_load_dwordx4 v[124:127], v[158:159], off offset:1024
	v_cvt_pk_bf16_f32 v132, v50, v51
	v_cvt_pk_bf16_f32 v133, v54, v55
	v_cvt_pk_bf16_f32 v134, v52, v53
	v_cvt_pk_bf16_f32 v135, v56, v57
	s_nop 1
	v_mfma_f32_32x32x16_bf16 v[2:17], v[144:147], v[132:135], v[2:17]
	s_waitcnt vmcnt(0)
	v_mfma_f32_32x32x16_bf16 v[18:33], v[124:127], v[132:135], v[18:33]
	global_load_dwordx4 v[132:135], v[158:159], off offset:3072
	v_cvt_pk_bf16_f32 v124, v76, v77
	v_cvt_pk_bf16_f32 v125, v96, v97
	v_cvt_pk_bf16_f32 v126, v40, v41
	v_cvt_pk_bf16_f32 v127, v46, v47
	s_nop 1
	v_mfma_f32_32x32x16_bf16 v[2:17], v[140:143], v[124:127], v[2:17]
	s_waitcnt vmcnt(0)
	v_mfma_f32_32x32x16_bf16 v[18:33], v[132:135], v[124:127], v[18:33]
	global_load_dwordx4 v[124:127], v[44:45], off offset:1024
	v_cvt_pk_bf16_f32 v132, v64, v65
	v_cvt_pk_bf16_f32 v133, v72, v73
	v_cvt_pk_bf16_f32 v134, v66, v67
	v_cvt_pk_bf16_f32 v135, v74, v75
	s_nop 1
	v_mfma_f32_32x32x16_bf16 v[2:17], v[136:139], v[132:135], v[2:17]
	global_load_dwordx4 v[136:139], v[44:45], off offset:2048
	v_mul_f32_e64 v44, v102, v156
	v_mul_f32_e64 v45, v103, v156
	s_waitcnt vmcnt(1)
	v_mfma_f32_32x32x16_bf16 v[18:33], v[124:127], v[132:135], v[18:33]
	v_cvt_pk_bf16_f32 v124, v112, v113
	v_cvt_pk_bf16_f32 v125, v70, v71
	v_cvt_pk_bf16_f32 v126, v44, v45
	v_cvt_pk_bf16_f32 v127, v68, v69
	s_waitcnt vmcnt(0)
	s_nop 0
	v_mfma_f32_32x32x16_bf16 v[2:17], v[136:139], v[124:127], v[2:17]
	v_mfma_f32_32x32x16_bf16 v[18:33], v[34:37], v[124:127], v[18:33]
	s_nop 10
	v_mul_f32_e32 v2, v0, v2
	v_mul_f32_e32 v3, v0, v3
	ds_write2st64_b32 v206, v2, v3 offset0:4 offset1:5
	v_mul_f32_e32 v18, v0, v18
	v_mul_f32_e32 v2, v0, v19
	ds_write2st64_b32 v206, v18, v2 offset0:20 offset1:21
	v_mul_f32_e32 v2, v0, v4
	v_mul_f32_e32 v4, v0, v5
	v_mul_f32_e32 v3, v0, v20
	ds_write2st64_b32 v206, v2, v4 offset0:6 offset1:7
	v_mul_f32_e32 v2, v0, v21
	ds_write2st64_b32 v206, v3, v2 offset0:22 offset1:23
	v_mul_f32_e32 v2, v0, v6
	v_mul_f32_e32 v4, v0, v7
	v_mul_f32_e32 v3, v0, v22
	ds_write2st64_b32 v206, v2, v4 offset0:8 offset1:9
	v_mul_f32_e32 v2, v0, v23
	ds_write2st64_b32 v206, v3, v2 offset0:24 offset1:25
	v_mul_f32_e32 v2, v0, v8
	v_mul_f32_e32 v4, v0, v9
	v_mul_f32_e32 v3, v0, v24
	ds_write2st64_b32 v206, v2, v4 offset0:10 offset1:11
	v_mul_f32_e32 v2, v0, v25
	ds_write2st64_b32 v206, v3, v2 offset0:26 offset1:27
	v_mul_f32_e32 v2, v0, v10
	v_mul_f32_e32 v4, v0, v11
	v_mul_f32_e32 v3, v0, v26
	ds_write2st64_b32 v206, v2, v4 offset0:12 offset1:13
	v_mul_f32_e32 v2, v0, v27
	ds_write2st64_b32 v206, v3, v2 offset0:28 offset1:29
	v_mul_f32_e32 v2, v0, v12
	v_mul_f32_e32 v4, v0, v13
	v_mul_f32_e32 v3, v0, v28
	ds_write2st64_b32 v206, v2, v4 offset0:14 offset1:15
	v_mul_f32_e32 v2, v0, v29
	ds_write2st64_b32 v206, v3, v2 offset0:30 offset1:31
	v_mul_f32_e32 v2, v0, v14
	v_mul_f32_e32 v4, v0, v15
	v_mul_f32_e32 v3, v0, v30
	ds_write2st64_b32 v206, v2, v4 offset0:16 offset1:17
	v_mul_f32_e32 v2, v0, v31
	ds_bpermute_b32 v20, v205, v123
	ds_write2st64_b32 v206, v3, v2 offset0:32 offset1:33
	v_mul_f32_e32 v2, v0, v16
	v_mul_f32_e32 v3, v0, v32
	v_mul_f32_e32 v4, v0, v17
	v_mul_f32_e32 v0, v0, v33
	ds_write2st64_b32 v206, v3, v0 offset0:34 offset1:35
	v_xor_b32_e32 v3, 1, v235
	v_cmp_lt_i32_e32 vcc, v3, v131
	ds_write2st64_b32 v206, v2, v4 offset0:18 offset1:19
	v_add_f32_e32 v4, v122, v123
	v_cndmask_b32_e32 v3, v235, v3, vcc
	v_add_f32_e32 v6, v120, v121
	v_cmp_gt_u32_e32 vcc, 32, v188
	v_add_f32_e32 v4, v6, v4
	v_lshlrev_b32_e32 v3, 2, v3
	s_waitcnt lgkmcnt(3)
	v_cndmask_b32_e64 v6, v20, 0, vcc
	v_add_f32_e32 v4, v6, v4
	ds_bpermute_b32 v6, v3, v4
	v_xor_b32_e32 v7, 2, v235
	v_cmp_lt_i32_e64 s[0:1], v7, v131
	ds_bpermute_b32 v19, v205, v117
	ds_bpermute_b32 v18, v205, v115
	v_cndmask_b32_e64 v7, v235, v7, s[0:1]
	v_lshlrev_b32_e32 v7, 2, v7
	s_waitcnt lgkmcnt(2)
	v_add_f32_e32 v21, v4, v6
	ds_bpermute_b32 v17, v205, v105
	ds_bpermute_b32 v16, v205, v61
	ds_bpermute_b32 v15, v205, v63
	ds_bpermute_b32 v14, v205, v99
	ds_bpermute_b32 v13, v205, v49
	ds_bpermute_b32 v12, v205, v55
	ds_bpermute_b32 v11, v205, v57
	ds_bpermute_b32 v10, v205, v97
	ds_bpermute_b32 v9, v205, v47
	ds_bpermute_b32 v8, v205, v73
	ds_bpermute_b32 v5, v205, v75
	ds_bpermute_b32 v0, v205, v71
	ds_bpermute_b32 v2, v205, v69
	ds_bpermute_b32 v22, v7, v21
	v_lshlrev_b32_e32 v4, 5, v129
	v_add_u32_e32 v6, v4, v196
	v_lshl_add_u32 v6, v6, 2, s83
	s_and_saveexec_b64 s[0:1], s[8:9]
	s_cbranch_execz .LBB0_1568
	s_waitcnt lgkmcnt(0)
	v_add_f32_e32 v21, v21, v22
	ds_write_b32 v6, v21

	.amdhsa_kernel _Z14fwd_megakernel6Params
		.amdhsa_group_segment_fixed_size 0
		.amdhsa_private_segment_fixed_size 0
		.amdhsa_kernarg_size 392
		.amdhsa_user_sgpr_count 2
		.amdhsa_user_sgpr_dispatch_ptr 0
		.amdhsa_user_sgpr_queue_ptr 0
		.amdhsa_user_sgpr_kernarg_segment_ptr 1
		.amdhsa_user_sgpr_dispatch_id 0
		.amdhsa_user_sgpr_kernarg_preload_length 0
		.amdhsa_user_sgpr_kernarg_preload_offset 0
		.amdhsa_user_sgpr_private_segment_size 0
		.amdhsa_uses_dynamic_stack 0
		.amdhsa_enable_private_segment 0
		.amdhsa_system_sgpr_workgroup_id_x 1
		.amdhsa_system_sgpr_workgroup_id_y 0
		.amdhsa_system_sgpr_workgroup_id_z 0
		.amdhsa_system_sgpr_workgroup_info 0
		.amdhsa_system_vgpr_workitem_id 2
		.amdhsa_next_free_vgpr 256
		.amdhsa_next_free_sgpr 102
		.amdhsa_accum_offset 256
		.amdhsa_reserve_vcc 1
		.amdhsa_float_round_mode_32 0
		.amdhsa_float_round_mode_16_64 0
		.amdhsa_float_denorm_mode_32 3
		.amdhsa_float_denorm_mode_16_64 3
		.amdhsa_dx10_clamp 1
		.amdhsa_ieee_mode 1
		.amdhsa_fp16_overflow 0
		.amdhsa_tg_split 0
		.amdhsa_exception_fp_ieee_invalid_op 0
		.amdhsa_exception_fp_denorm_src 0
		.amdhsa_exception_fp_ieee_div_zero 0
		.amdhsa_exception_fp_ieee_overflow 0
		.amdhsa_exception_fp_ieee_underflow 0
		.amdhsa_exception_fp_ieee_inexact 0
		.amdhsa_exception_int_div_zero 0
	.end_amdhsa_kernel

amdhsa.kernels:
  - .agpr_count:     0
    .args:
      - .offset:         0
        .size:           136
        .value_kind:     by_value
      - .offset:         136
        .size:           4
        .value_kind:     hidden_block_count_x
      - .offset:         140
        .size:           4
        .value_kind:     hidden_block_count_y
      - .offset:         144
        .size:           4
        .value_kind:     hidden_block_count_z
      - .offset:         148
        .size:           2
        .value_kind:     hidden_group_size_x
      - .offset:         150
        .size:           2
        .value_kind:     hidden_group_size_y
      - .offset:         152
        .size:           2
        .value_kind:     hidden_group_size_z
      - .offset:         154
        .size:           2
        .value_kind:     hidden_remainder_x
      - .offset:         156
        .size:           2
        .value_kind:     hidden_remainder_y
      - .offset:         158
        .size:           2
        .value_kind:     hidden_remainder_z
      - .offset:         176
        .size:           8
        .value_kind:     hidden_global_offset_x
      - .offset:         184
        .size:           8
        .value_kind:     hidden_global_offset_y
      - .offset:         192
        .size:           8
        .value_kind:     hidden_global_offset_z
      - .offset:         200
        .size:           2
        .value_kind:     hidden_grid_dims
      - .offset:         224
        .size:           8
        .value_kind:     hidden_multigrid_sync_arg
      - .offset:         256
        .size:           4
        .value_kind:     hidden_dynamic_lds_size
    .group_segment_fixed_size: 0
    .kernarg_segment_align: 8
    .kernarg_segment_size: 392
    .language:       OpenCL C
    .language_version:
      - 2
      - 0
    .max_flat_workgroup_size: 512
    .name:           _Z14fwd_megakernel6Params
    .private_segment_fixed_size: 0
    .sgpr_count:     108
    .sgpr_spill_count: 224
    .symbol:         _Z14fwd_megakernel6Params.kd
    .uniform_work_group_size: 1
    .uses_dynamic_stack: false
    .vgpr_count:     256
    .vgpr_spill_count: 0
    .wavefront_size: 64
